# v41 + LDS-DMA in saddr form (no per-DMA 64-bit VALU address adds) and immediate-offset LDS reads in all 5 GEMM main loops
# speedup vs baseline: 1.0191x; 1.0077x over previous
.LBB0_174:
	v_readlane_b32 s50, v252, 47
	s_add_u32 s28, s52, 0x40080
	v_mov_b32_e32 v133, v143
	v_readlane_b32 s51, v252, 48
	s_addc_u32 s29, s53, 0
	s_add_i32 m0, s58, 0x18000
	v_lshl_add_u64 v[0:1], v[0:1], 0, s[22:23]
	v_lshl_add_u64 v[12:13], s[50:51], 0, v[132:133]
	v_mov_b32_e32 v131, v143
	s_waitcnt vmcnt(2)
	s_barrier
	global_load_lds_dwordx4 v[0:1], off
	v_lshl_add_u64 v[0:1], v[2:3], 0, s[22:23]
	s_add_i32 m0, s58, 0x1a000
	s_add_i32 s62, s58, 0x8000
	v_lshl_add_u64 v[14:15], s[50:51], 0, v[130:131]
	global_load_lds_dwordx4 v[0:1], off
	v_lshl_add_u64 v[0:1], v[12:13], 0, s[22:23]
	s_mov_b32 m0, s62
	s_add_i32 s63, s58, 0xa000
	global_load_lds_dwordx4 v[0:1], off
	v_lshl_add_u64 v[0:1], v[14:15], 0, s[22:23]
	s_mov_b32 m0, s63
	v_readlane_b32 s4, v252, 43
	global_load_lds_dwordx4 v[0:1], off
	s_add_i32 m0, s58, 0x1c000
	v_lshl_add_u64 v[0:1], s[28:29], 0, v[142:143]
	global_load_lds_dwordx4 v[0:1], off
	v_lshl_add_u64 v[0:1], s[28:29], 0, v[128:129]
	s_add_i32 m0, s58, 0x1e000
	s_lshl_b32 s28, s40, 13
	global_load_lds_dwordx4 v[0:1], off
	v_lshrrev_b32_e32 v1, 1, v4
	v_and_b32_e32 v1, 24, v1
	v_and_b32_e32 v0, 15, v4
	v_lshlrev_b32_e32 v2, 1, v1
	v_lshl_or_b32 v140, s40, 6, v0
	v_lshl_or_b32 v0, v0, 6, v2
	v_lshlrev_b32_e32 v2, 2, v4
	v_and_b32_e32 v2, 32, v2
	v_bitop3_b32 v3, v0, s28, v2 bitop3:0xde
	s_lshl_b32 s28, s37, 5
	s_and_b32 s28, s28, 0x60
	s_lshl_b32 s29, s28, 7
	v_bitop3_b32 v141, v0, s29, v2 bitop3:0xde
	v_add_u32_e32 v254, 0x10000, v141
	v_lshlrev_b32_e32 v0, 14, v9
	v_and_b32_e32 v0, 0xffff8000, v0
	v_or_b32_e32 v156, s28, v1
	v_lshl_add_u32 v0, v8, 11, v0
	v_and_b32_e32 v1, 1, v9
	v_lshl_or_b32 v0, v1, 6, v0
	v_lshl_add_u32 v134, v10, 1, v0
	v_lshlrev_b32_e32 v0, 14, v5
	v_and_b32_e32 v0, 0xffff8000, v0
	s_waitcnt vmcnt(6)
	v_lshl_add_u32 v0, v6, 11, v0
	v_and_b32_e32 v1, 1, v5
	s_cmpk_lt_u32 s36, 0x100
	v_lshl_or_b32 v0, v1, 6, v0
	s_cselect_b64 s[40:41], -1, 0
	v_mov_b32_e32 v135, v143
	v_lshl_add_u32 v136, v7, 1, v0
	v_mov_b32_e32 v137, v143
	s_mov_b32 s64, 0
	v_add_u32_e32 v157, 0, v3
	v_readlane_b32 s65, v252, 42
	s_mov_b32 s66, s4
	s_movk_i32 s4, 0x161
	s_barrier
	v_readlane_b32 s5, v252, 44
	s_branch .LBB0_177

.LBB0_180:
	s_add_u32 s28, s50, 0xfffc0080
	s_addc_u32 s29, s51, -1
	s_add_i32 s72, 0, 0x10000
	s_cmp_eq_u32 s71, 12
	s_cselect_b32 s55, s45, s29
	s_cselect_b32 s54, s67, s28
	s_cselect_b32 s53, s43, s70
	s_cselect_b32 s52, s68, s69
	s_add_i32 s73, 0, 0x14000
	ds_read_b128 v[158:161], v254
	ds_read_b128 v[162:165], v254 offset:1024
	ds_read_b128 v[166:169], v254 offset:2048
	ds_read_b128 v[170:173], v254 offset:3072
	ds_read_b128 v[174:177], v254 offset:16384
	ds_read_b128 v[178:181], v254 offset:17408
	ds_read_b128 v[182:185], v254 offset:18432
	ds_read_b128 v[186:189], v254 offset:19456
	s_add_i32 m0, s58, 0xc000
	ds_read_b128 v[190:193], v157
	ds_read_b128 v[194:197], v157 offset:1024
	ds_read_b128 v[198:201], v157 offset:2048
	ds_read_b128 v[202:205], v157 offset:3072
	ds_read_b128 v[206:209], v157 offset:4096
	ds_read_b128 v[210:213], v157 offset:5120
	ds_read_b128 v[214:217], v157 offset:6144
	ds_read_b128 v[218:221], v157 offset:7168
	global_load_lds_dwordx4 v134, s[50:51]
	s_add_i32 m0, s58, 0xe000
	s_nop 0
	global_load_lds_dwordx4 v136, s[50:51]
	s_waitcnt vmcnt(8)
	s_waitcnt lgkmcnt(0)
	s_barrier
	s_setprio 1
	s_waitcnt lgkmcnt(0)
	v_mfma_f32_16x16x32_bf16 v[124:127], v[158:161], v[190:193], v[124:127]
	v_mfma_f32_16x16x32_bf16 v[116:119], v[166:169], v[190:193], v[116:119]
	v_mfma_f32_16x16x32_bf16 v[108:111], v[158:161], v[198:201], v[108:111]
	v_mfma_f32_16x16x32_bf16 v[100:103], v[166:169], v[198:201], v[100:103]
	v_mfma_f32_16x16x32_bf16 v[92:95], v[158:161], v[206:209], v[92:95]
	v_mfma_f32_16x16x32_bf16 v[84:87], v[166:169], v[206:209], v[84:87]
	v_mfma_f32_16x16x32_bf16 v[76:79], v[158:161], v[214:217], v[76:79]
	v_mfma_f32_16x16x32_bf16 v[68:71], v[166:169], v[214:217], v[68:71]
	v_mfma_f32_16x16x32_bf16 v[124:127], v[162:165], v[194:197], v[124:127]
	v_mfma_f32_16x16x32_bf16 v[116:119], v[170:173], v[194:197], v[116:119]
	v_mfma_f32_16x16x32_bf16 v[108:111], v[162:165], v[202:205], v[108:111]
	v_mfma_f32_16x16x32_bf16 v[100:103], v[170:173], v[202:205], v[100:103]
	v_mfma_f32_16x16x32_bf16 v[92:95], v[162:165], v[210:213], v[92:95]
	v_mfma_f32_16x16x32_bf16 v[84:87], v[170:173], v[210:213], v[84:87]
	v_mfma_f32_16x16x32_bf16 v[76:79], v[162:165], v[218:221], v[76:79]
	v_mfma_f32_16x16x32_bf16 v[68:71], v[170:173], v[218:221], v[68:71]
	v_mfma_f32_16x16x32_bf16 v[120:123], v[174:177], v[190:193], v[120:123]
	v_mfma_f32_16x16x32_bf16 v[112:115], v[182:185], v[190:193], v[112:115]
	v_mfma_f32_16x16x32_bf16 v[104:107], v[174:177], v[198:201], v[104:107]
	v_mfma_f32_16x16x32_bf16 v[96:99], v[182:185], v[198:201], v[96:99]
	v_mfma_f32_16x16x32_bf16 v[88:91], v[174:177], v[206:209], v[88:91]
	v_mfma_f32_16x16x32_bf16 v[80:83], v[182:185], v[206:209], v[80:83]
	v_mfma_f32_16x16x32_bf16 v[72:75], v[174:177], v[214:217], v[72:75]
	v_mfma_f32_16x16x32_bf16 v[64:67], v[182:185], v[214:217], v[64:67]
	v_mfma_f32_16x16x32_bf16 v[120:123], v[178:181], v[194:197], v[120:123]
	v_mfma_f32_16x16x32_bf16 v[112:115], v[186:189], v[194:197], v[112:115]
	v_mfma_f32_16x16x32_bf16 v[104:107], v[178:181], v[202:205], v[104:107]
	v_mfma_f32_16x16x32_bf16 v[96:99], v[186:189], v[202:205], v[96:99]
	v_mfma_f32_16x16x32_bf16 v[88:91], v[178:181], v[210:213], v[88:91]
	v_mfma_f32_16x16x32_bf16 v[80:83], v[186:189], v[210:213], v[80:83]
	v_mfma_f32_16x16x32_bf16 v[72:75], v[178:181], v[218:221], v[72:75]
	v_mfma_f32_16x16x32_bf16 v[64:67], v[186:189], v[218:221], v[64:67]
	s_setprio 0
	s_barrier
	s_add_i32 s28, s72, s57
	s_mov_b32 m0, s28
	ds_read_b128 v[190:193], v157 offset:16384
	ds_read_b128 v[194:197], v157 offset:17408
	ds_read_b128 v[198:201], v157 offset:18432
	ds_read_b128 v[202:205], v157 offset:19456
	ds_read_b128 v[206:209], v157 offset:20480
	ds_read_b128 v[210:213], v157 offset:21504
	ds_read_b128 v[214:217], v157 offset:22528
	ds_read_b128 v[218:221], v157 offset:23552
	global_load_lds_dwordx4 v142, s[52:53]
	s_add_u32 s98, s52, 0x80
	s_addc_u32 s99, s53, 0
	s_add_i32 m0, s28, 0x2000
	s_add_u32 s28, s52, 0x40000
	s_addc_u32 s29, s53, 0
	s_add_i32 s72, s73, s57
	global_load_lds_dwordx4 v128, s[52:53]
	s_mov_b32 m0, s72
	s_nop 0
	global_load_lds_dwordx4 v142, s[28:29]
	s_add_i32 m0, s72, 0x2000
	s_nop 0
	global_load_lds_dwordx4 v128, s[28:29]
	s_mov_b32 m0, s58
	s_nop 0
	global_load_lds_dwordx4 v132, s[54:55]
	s_add_u32 s100, s54, 0x80
	s_addc_u32 s101, s55, 0
	s_mov_b32 m0, s59
	s_nop 0
	global_load_lds_dwordx4 v130, s[54:55]
	s_waitcnt vmcnt(8)
	s_waitcnt lgkmcnt(0)
	s_barrier
	s_setprio 1
	s_waitcnt lgkmcnt(0)
	v_mfma_f32_16x16x32_bf16 v[60:63], v[158:161], v[190:193], v[60:63]
	v_mfma_f32_16x16x32_bf16 v[52:55], v[166:169], v[190:193], v[52:55]
	v_mfma_f32_16x16x32_bf16 v[44:47], v[158:161], v[198:201], v[44:47]
	v_mfma_f32_16x16x32_bf16 v[36:39], v[166:169], v[198:201], v[36:39]
	v_mfma_f32_16x16x32_bf16 v[28:31], v[158:161], v[206:209], v[28:31]
	v_mfma_f32_16x16x32_bf16 v[20:23], v[166:169], v[206:209], v[20:23]
	v_mfma_f32_16x16x32_bf16 v[12:15], v[158:161], v[214:217], v[12:15]
	v_mfma_f32_16x16x32_bf16 v[4:7], v[166:169], v[214:217], v[4:7]
	v_mfma_f32_16x16x32_bf16 v[60:63], v[162:165], v[194:197], v[60:63]
	v_mfma_f32_16x16x32_bf16 v[52:55], v[170:173], v[194:197], v[52:55]
	v_mfma_f32_16x16x32_bf16 v[44:47], v[162:165], v[202:205], v[44:47]
	v_mfma_f32_16x16x32_bf16 v[36:39], v[170:173], v[202:205], v[36:39]
	v_mfma_f32_16x16x32_bf16 v[28:31], v[162:165], v[210:213], v[28:31]
	v_mfma_f32_16x16x32_bf16 v[20:23], v[170:173], v[210:213], v[20:23]
	v_mfma_f32_16x16x32_bf16 v[12:15], v[162:165], v[218:221], v[12:15]
	v_mfma_f32_16x16x32_bf16 v[4:7], v[170:173], v[218:221], v[4:7]
	v_mfma_f32_16x16x32_bf16 v[56:59], v[174:177], v[190:193], v[56:59]
	v_mfma_f32_16x16x32_bf16 v[48:51], v[182:185], v[190:193], v[48:51]
	v_mfma_f32_16x16x32_bf16 v[40:43], v[174:177], v[198:201], v[40:43]
	v_mfma_f32_16x16x32_bf16 v[32:35], v[182:185], v[198:201], v[32:35]
	v_mfma_f32_16x16x32_bf16 v[24:27], v[174:177], v[206:209], v[24:27]
	v_mfma_f32_16x16x32_bf16 v[16:19], v[182:185], v[206:209], v[16:19]
	v_mfma_f32_16x16x32_bf16 v[8:11], v[174:177], v[214:217], v[8:11]
	v_mfma_f32_16x16x32_bf16 v[0:3], v[182:185], v[214:217], v[0:3]
	v_mfma_f32_16x16x32_bf16 v[56:59], v[178:181], v[194:197], v[56:59]
	v_mfma_f32_16x16x32_bf16 v[48:51], v[186:189], v[194:197], v[48:51]
	v_mfma_f32_16x16x32_bf16 v[40:43], v[178:181], v[202:205], v[40:43]
	v_mfma_f32_16x16x32_bf16 v[32:35], v[186:189], v[202:205], v[32:35]
	v_mfma_f32_16x16x32_bf16 v[24:27], v[178:181], v[210:213], v[24:27]
	v_mfma_f32_16x16x32_bf16 v[16:19], v[186:189], v[210:213], v[16:19]
	v_mfma_f32_16x16x32_bf16 v[8:11], v[178:181], v[218:221], v[8:11]
	v_mfma_f32_16x16x32_bf16 v[0:3], v[186:189], v[218:221], v[0:3]
	s_setprio 0
	s_barrier
	s_add_i32 s72, 0, 0x18000
	s_add_i32 s73, 0, 0x1c000
	ds_read_b128 v[158:161], v254 offset:32768
	ds_read_b128 v[162:165], v254 offset:33792
	ds_read_b128 v[166:169], v254 offset:34816
	ds_read_b128 v[170:173], v254 offset:35840
	ds_read_b128 v[174:177], v254 offset:49152
	ds_read_b128 v[178:181], v254 offset:50176
	ds_read_b128 v[182:185], v254 offset:51200
	ds_read_b128 v[186:189], v254 offset:52224
	s_add_u32 s28, s54, 0x40000
	s_addc_u32 s29, s55, 0
	s_mov_b32 m0, s60
	ds_read_b128 v[190:193], v157 offset:32768
	ds_read_b128 v[194:197], v157 offset:33792
	ds_read_b128 v[198:201], v157 offset:34816
	ds_read_b128 v[202:205], v157 offset:35840
	ds_read_b128 v[206:209], v157 offset:36864
	ds_read_b128 v[210:213], v157 offset:37888
	ds_read_b128 v[214:217], v157 offset:38912
	ds_read_b128 v[218:221], v157 offset:39936
	global_load_lds_dwordx4 v132, s[28:29]
	s_mov_b32 m0, s61
	s_nop 0
	global_load_lds_dwordx4 v130, s[28:29]
	s_waitcnt vmcnt(8)
	s_waitcnt lgkmcnt(0)
	s_barrier
	s_setprio 1
	s_waitcnt lgkmcnt(0)
	v_mfma_f32_16x16x32_bf16 v[124:127], v[158:161], v[190:193], v[124:127]
	v_mfma_f32_16x16x32_bf16 v[116:119], v[166:169], v[190:193], v[116:119]
	v_mfma_f32_16x16x32_bf16 v[108:111], v[158:161], v[198:201], v[108:111]
	v_mfma_f32_16x16x32_bf16 v[100:103], v[166:169], v[198:201], v[100:103]
	v_mfma_f32_16x16x32_bf16 v[92:95], v[158:161], v[206:209], v[92:95]
	v_mfma_f32_16x16x32_bf16 v[84:87], v[166:169], v[206:209], v[84:87]
	v_mfma_f32_16x16x32_bf16 v[76:79], v[158:161], v[214:217], v[76:79]
	v_mfma_f32_16x16x32_bf16 v[68:71], v[166:169], v[214:217], v[68:71]
	v_mfma_f32_16x16x32_bf16 v[124:127], v[162:165], v[194:197], v[124:127]
	v_mfma_f32_16x16x32_bf16 v[116:119], v[170:173], v[194:197], v[116:119]
	v_mfma_f32_16x16x32_bf16 v[108:111], v[162:165], v[202:205], v[108:111]
	v_mfma_f32_16x16x32_bf16 v[100:103], v[170:173], v[202:205], v[100:103]
	v_mfma_f32_16x16x32_bf16 v[92:95], v[162:165], v[210:213], v[92:95]
	v_mfma_f32_16x16x32_bf16 v[84:87], v[170:173], v[210:213], v[84:87]
	v_mfma_f32_16x16x32_bf16 v[76:79], v[162:165], v[218:221], v[76:79]
	v_mfma_f32_16x16x32_bf16 v[68:71], v[170:173], v[218:221], v[68:71]
	v_mfma_f32_16x16x32_bf16 v[120:123], v[174:177], v[190:193], v[120:123]
	v_mfma_f32_16x16x32_bf16 v[112:115], v[182:185], v[190:193], v[112:115]
	v_mfma_f32_16x16x32_bf16 v[104:107], v[174:177], v[198:201], v[104:107]
	v_mfma_f32_16x16x32_bf16 v[96:99], v[182:185], v[198:201], v[96:99]
	v_mfma_f32_16x16x32_bf16 v[88:91], v[174:177], v[206:209], v[88:91]
	v_mfma_f32_16x16x32_bf16 v[80:83], v[182:185], v[206:209], v[80:83]
	v_mfma_f32_16x16x32_bf16 v[72:75], v[174:177], v[214:217], v[72:75]
	v_mfma_f32_16x16x32_bf16 v[64:67], v[182:185], v[214:217], v[64:67]
	v_mfma_f32_16x16x32_bf16 v[120:123], v[178:181], v[194:197], v[120:123]
	v_mfma_f32_16x16x32_bf16 v[112:115], v[186:189], v[194:197], v[112:115]
	v_mfma_f32_16x16x32_bf16 v[104:107], v[178:181], v[202:205], v[104:107]
	v_mfma_f32_16x16x32_bf16 v[96:99], v[186:189], v[202:205], v[96:99]
	v_mfma_f32_16x16x32_bf16 v[88:91], v[178:181], v[210:213], v[88:91]
	v_mfma_f32_16x16x32_bf16 v[80:83], v[186:189], v[210:213], v[80:83]
	v_mfma_f32_16x16x32_bf16 v[72:75], v[178:181], v[218:221], v[72:75]
	v_mfma_f32_16x16x32_bf16 v[64:67], v[186:189], v[218:221], v[64:67]
	s_setprio 0
	s_barrier
	s_add_i32 s28, s72, s57
	s_mov_b32 m0, s28
	ds_read_b128 v[190:193], v157 offset:49152
	ds_read_b128 v[194:197], v157 offset:50176
	ds_read_b128 v[198:201], v157 offset:51200
	ds_read_b128 v[202:205], v157 offset:52224
	ds_read_b128 v[206:209], v157 offset:53248
	ds_read_b128 v[210:213], v157 offset:54272
	ds_read_b128 v[214:217], v157 offset:55296
	ds_read_b128 v[218:221], v157 offset:56320
	global_load_lds_dwordx4 v142, s[98:99]
	s_add_i32 m0, s28, 0x2000
	s_add_u32 s28, s52, 0x40080
	s_addc_u32 s29, s53, 0
	s_add_i32 s52, s73, s57
	global_load_lds_dwordx4 v128, s[98:99]
	s_mov_b32 m0, s52
	s_nop 0
	global_load_lds_dwordx4 v142, s[28:29]
	s_add_i32 m0, s52, 0x2000
	s_nop 0
	global_load_lds_dwordx4 v128, s[28:29]
	s_mov_b32 m0, s62
	s_nop 0
	global_load_lds_dwordx4 v132, s[100:101]
	s_mov_b32 m0, s63
	s_nop 0
	global_load_lds_dwordx4 v130, s[100:101]
	s_waitcnt vmcnt(8)
	s_waitcnt lgkmcnt(0)
	s_barrier
	s_setprio 1
	s_waitcnt lgkmcnt(0)
	v_mfma_f32_16x16x32_bf16 v[60:63], v[158:161], v[190:193], v[60:63]
	v_mfma_f32_16x16x32_bf16 v[52:55], v[166:169], v[190:193], v[52:55]
	v_mfma_f32_16x16x32_bf16 v[44:47], v[158:161], v[198:201], v[44:47]
	v_mfma_f32_16x16x32_bf16 v[36:39], v[166:169], v[198:201], v[36:39]
	v_mfma_f32_16x16x32_bf16 v[28:31], v[158:161], v[206:209], v[28:31]
	v_mfma_f32_16x16x32_bf16 v[20:23], v[166:169], v[206:209], v[20:23]
	v_mfma_f32_16x16x32_bf16 v[12:15], v[158:161], v[214:217], v[12:15]
	v_mfma_f32_16x16x32_bf16 v[4:7], v[166:169], v[214:217], v[4:7]
	v_mfma_f32_16x16x32_bf16 v[60:63], v[162:165], v[194:197], v[60:63]
	v_mfma_f32_16x16x32_bf16 v[52:55], v[170:173], v[194:197], v[52:55]
	v_mfma_f32_16x16x32_bf16 v[44:47], v[162:165], v[202:205], v[44:47]
	v_mfma_f32_16x16x32_bf16 v[36:39], v[170:173], v[202:205], v[36:39]
	v_mfma_f32_16x16x32_bf16 v[28:31], v[162:165], v[210:213], v[28:31]
	v_mfma_f32_16x16x32_bf16 v[20:23], v[170:173], v[210:213], v[20:23]
	v_mfma_f32_16x16x32_bf16 v[12:15], v[162:165], v[218:221], v[12:15]
	v_mfma_f32_16x16x32_bf16 v[4:7], v[170:173], v[218:221], v[4:7]
	v_mfma_f32_16x16x32_bf16 v[56:59], v[174:177], v[190:193], v[56:59]
	v_mfma_f32_16x16x32_bf16 v[48:51], v[182:185], v[190:193], v[48:51]
	v_mfma_f32_16x16x32_bf16 v[40:43], v[174:177], v[198:201], v[40:43]
	v_mfma_f32_16x16x32_bf16 v[32:35], v[182:185], v[198:201], v[32:35]
	v_mfma_f32_16x16x32_bf16 v[24:27], v[174:177], v[206:209], v[24:27]
	v_mfma_f32_16x16x32_bf16 v[16:19], v[182:185], v[206:209], v[16:19]
	v_mfma_f32_16x16x32_bf16 v[8:11], v[174:177], v[214:217], v[8:11]
	v_mfma_f32_16x16x32_bf16 v[0:3], v[182:185], v[214:217], v[0:3]
	v_mfma_f32_16x16x32_bf16 v[56:59], v[178:181], v[194:197], v[56:59]
	v_mfma_f32_16x16x32_bf16 v[48:51], v[186:189], v[194:197], v[48:51]
	v_mfma_f32_16x16x32_bf16 v[40:43], v[178:181], v[202:205], v[40:43]
	v_mfma_f32_16x16x32_bf16 v[32:35], v[186:189], v[202:205], v[32:35]
	v_mfma_f32_16x16x32_bf16 v[24:27], v[178:181], v[210:213], v[24:27]
	v_mfma_f32_16x16x32_bf16 v[16:19], v[186:189], v[210:213], v[16:19]
	v_mfma_f32_16x16x32_bf16 v[8:11], v[178:181], v[218:221], v[8:11]
	v_mfma_f32_16x16x32_bf16 v[0:3], v[186:189], v[218:221], v[0:3]
	s_setprio 0
	s_barrier
	s_add_i32 s71, s71, 2
	s_add_u32 s50, s50, 0x100
	s_addc_u32 s51, s51, 0
	s_add_u32 s69, s69, 0x100
	s_addc_u32 s70, s70, 0
	s_cmp_gt_u32 s71, 13
	s_cbranch_scc0 .LBB0_180
	s_and_b64 vcc, exec, s[40:41]
	s_cbranch_vccz .LBB0_183
	s_barrier

.LBB0_262:
	v_bfe_u32 v17, v16, 4, 2
	v_and_b32_e32 v18, 15, v16
	v_lshlrev_b32_e32 v19, 4, v17
	v_lshlrev_b32_e32 v16, 2, v16
	v_lshl_or_b32 v158, s37, 6, v18
	v_lshl_or_b32 v18, v18, 6, v19
	s_lshl_b32 s28, s37, 13
	v_and_b32_e32 v16, 32, v16
	v_bitop3_b32 v19, v18, s28, v16 bitop3:0xde
	s_lshl_b32 s28, s40, 5
	v_readlane_b32 s4, v252, 18
	s_and_b32 s37, s28, 0x60
	v_readlane_b32 s5, v252, 19
	v_readlane_b32 s6, v252, 20
	v_readlane_b32 s7, v252, 21
	v_readlane_b32 s8, v252, 22
	v_readlane_b32 s9, v252, 23
	v_readlane_b32 s10, v252, 24
	v_readlane_b32 s11, v252, 25
	v_readlane_b32 s12, v252, 26
	v_readlane_b32 s13, v252, 27
	v_readlane_b32 s14, v252, 28
	v_readlane_b32 s15, v252, 29
	v_readlane_b32 s16, v252, 30
	v_readlane_b32 s17, v252, 31
	v_readlane_b32 s18, v252, 32
	v_readlane_b32 s19, v252, 33
	s_lshl_b32 s28, s37, 7
	s_mov_b64 s[40:41], s[4:5]
	v_readlane_b32 s4, v252, 0
	v_bitop3_b32 v230, v18, s28, v16 bitop3:0xde
	v_add_u32_e32 v254, 0x10000, v230
	s_and_b64 s[28:29], s[38:39], exec
	v_readlane_b32 s16, v252, 12
	v_readlane_b32 s17, v252, 13
	s_cselect_b32 s72, s41, s17
	s_cselect_b32 s73, s40, s16
	s_add_i32 m0, s68, 0x18000
	v_lshl_add_u64 v[6:7], v[6:7], 0, s[22:23]
	s_waitcnt vmcnt(2)
	s_barrier
	global_load_lds_dwordx4 v[6:7], off
	v_lshl_add_u64 v[4:5], v[4:5], 0, s[22:23]
	s_add_i32 m0, s68, 0x1a000
	s_add_i32 s74, s68, 0x8000
	s_add_i32 s75, s68, 0xa000
	global_load_lds_dwordx4 v[4:5], off
	v_lshl_add_u64 v[0:1], v[0:1], 0, s[22:23]
	s_mov_b32 m0, s74
	s_add_u32 s28, s62, 0xb0080
	global_load_lds_dwordx4 v[0:1], off
	v_lshl_add_u64 v[0:1], v[2:3], 0, s[22:23]
	s_mov_b32 m0, s75
	s_addc_u32 s29, s63, 0
	global_load_lds_dwordx4 v[0:1], off
	s_add_i32 m0, s68, 0x1c000
	v_lshl_add_u64 v[0:1], s[28:29], 0, v[142:143]
	global_load_lds_dwordx4 v[0:1], off
	v_lshl_add_u64 v[0:1], s[28:29], 0, v[156:157]
	s_add_i32 m0, s68, 0x1e000
	v_ashrrev_i32_e32 v159, 31, v158
	global_load_lds_dwordx4 v[0:1], off
	v_or_b32_e32 v0, 16, v158
	v_ashrrev_i32_e32 v1, 31, v0
	v_lshlrev_b64 v[164:165], 10, v[0:1]
	v_or_b32_e32 v0, 32, v158
	v_lshlrev_b64 v[160:161], 10, v[158:159]
	s_mov_b64 s[28:29], 0x20000
	v_ashrrev_i32_e32 v1, 31, v0
	v_lshl_add_u64 v[162:163], v[160:161], 0, s[28:29]
	v_lshlrev_b64 v[166:167], 10, v[0:1]
	v_or_b32_e32 v0, 48, v158
	s_mov_b64 s[28:29], 0x24000
	v_readlane_b32 s5, v252, 1
	v_ashrrev_i32_e32 v1, 31, v0
	v_lshl_add_u64 v[170:171], v[160:161], 0, s[28:29]
	s_mov_b64 s[28:29], 0x28000
	s_movk_i32 s4, 0xb00
	v_lshlrev_b64 v[168:169], 10, v[0:1]
	v_lshl_add_u64 v[172:173], v[160:161], 0, s[28:29]
	s_mov_b64 s[28:29], 0x2c000
	v_lshrrev_b32_e32 v1, 1, v8
	v_mul_lo_u32 v0, v10, s4
	s_mov_b32 s5, 0xb000
	v_lshl_add_u64 v[174:175], v[160:161], 0, s[28:29]
	v_mad_u64_u32 v[0:1], s[28:29], v1, s5, v[0:1]
	v_readlane_b32 s6, v252, 2
	v_readlane_b32 s7, v252, 3
	v_or_b32_e32 v0, v0, v9
	v_add_lshl_u32 v0, v0, v11, 1
	v_mov_b32_e32 v1, v143
	s_mov_b64 s[6:7], 0xb0080
	v_lshl_add_u64 v[176:177], v[0:1], 0, s[6:7]
	v_lshrrev_b32_e32 v1, 1, v12
	v_mul_lo_u32 v0, v14, s4
	v_mad_u64_u32 v[0:1], s[28:29], v1, s5, v[0:1]
	s_waitcnt vmcnt(6)
	v_or_b32_e32 v0, v0, v13
	s_cmpk_lt_u32 s36, 0x100
	v_add_lshl_u32 v0, v0, v15, 1
	v_mov_b32_e32 v1, v143
	s_cselect_b64 s[52:53], -1, 0
	v_lshl_or_b32 v159, v17, 2, s37
	v_lshl_add_u64 v[178:179], v[0:1], 0, s[6:7]
	s_mov_b32 s76, 0
	v_add_u32_e32 v231, 0, v19
	v_readlane_b32 s8, v252, 4
	v_readlane_b32 s9, v252, 5
	v_readlane_b32 s10, v252, 6
	v_readlane_b32 s11, v252, 7
	v_readlane_b32 s12, v252, 8
	v_readlane_b32 s13, v252, 9
	v_readlane_b32 s14, v252, 10
	v_readlane_b32 s15, v252, 11
	v_readlane_b32 s18, v252, 14
	v_readlane_b32 s19, v252, 15
	s_barrier
	s_branch .LBB0_265

.LBB0_276:
	s_add_u32 s40, s60, 0x100
	s_addc_u32 s41, s61, 0
	s_add_i32 s28, 0, 0x10000
	s_cmp_eq_u32 s59, 40
	s_cselect_b32 s65, s55, s41
	s_cselect_b32 s64, s54, s40
	s_cselect_b32 s63, s57, s37
	s_cselect_b32 s62, s56, s36
	s_add_i32 s79, 0, 0x14000
	ds_read_b128 v[108:111], v254
	ds_read_b128 v[130:133], v254 offset:1024
	ds_read_b128 v[134:137], v254 offset:2048
	ds_read_b128 v[180:183], v254 offset:3072
	ds_read_b128 v[184:187], v254 offset:16384
	ds_read_b128 v[188:191], v254 offset:17408
	ds_read_b128 v[192:195], v254 offset:18432
	ds_read_b128 v[196:199], v254 offset:19456
	s_add_i32 m0, s68, 0xc000
	ds_read_b128 v[200:203], v231
	ds_read_b128 v[204:207], v231 offset:1024
	ds_read_b128 v[208:211], v231 offset:2048
	ds_read_b128 v[212:215], v231 offset:3072
	ds_read_b128 v[216:219], v231 offset:4096
	ds_read_b128 v[232:235], v231 offset:5120
	ds_read_b128 v[236:239], v231 offset:6144
	ds_read_b128 v[240:243], v231 offset:7168
	global_load_lds_dwordx4 v176, s[60:61]
	s_add_i32 m0, s68, 0xe000
	s_nop 0
	global_load_lds_dwordx4 v178, s[60:61]
	s_waitcnt vmcnt(8)
	s_waitcnt lgkmcnt(0)
	s_barrier
	s_setprio 1
	s_waitcnt lgkmcnt(0)
	v_mfma_f32_16x16x32_bf16 v[138:141], v[108:111], v[200:203], v[138:141]
	v_mfma_f32_16x16x32_bf16 v[92:95], v[134:137], v[200:203], v[92:95]
	v_mfma_f32_16x16x32_bf16 v[126:129], v[108:111], v[208:211], v[126:129]
	v_mfma_f32_16x16x32_bf16 v[88:91], v[134:137], v[208:211], v[88:91]
	v_mfma_f32_16x16x32_bf16 v[122:125], v[108:111], v[216:219], v[122:125]
	v_mfma_f32_16x16x32_bf16 v[84:87], v[134:137], v[216:219], v[84:87]
	v_mfma_f32_16x16x32_bf16 v[118:121], v[108:111], v[236:239], v[118:121]
	v_mfma_f32_16x16x32_bf16 v[80:83], v[134:137], v[236:239], v[80:83]
	v_mfma_f32_16x16x32_bf16 v[138:141], v[130:133], v[204:207], v[138:141]
	v_mfma_f32_16x16x32_bf16 v[92:95], v[180:183], v[204:207], v[92:95]
	v_mfma_f32_16x16x32_bf16 v[126:129], v[130:133], v[212:215], v[126:129]
	v_mfma_f32_16x16x32_bf16 v[88:91], v[180:183], v[212:215], v[88:91]
	v_mfma_f32_16x16x32_bf16 v[122:125], v[130:133], v[232:235], v[122:125]
	v_mfma_f32_16x16x32_bf16 v[84:87], v[180:183], v[232:235], v[84:87]
	v_mfma_f32_16x16x32_bf16 v[118:121], v[130:133], v[240:243], v[118:121]
	v_mfma_f32_16x16x32_bf16 v[80:83], v[180:183], v[240:243], v[80:83]
	v_mfma_f32_16x16x32_bf16 v[60:63], v[184:187], v[200:203], v[60:63]
	v_mfma_f32_16x16x32_bf16 v[28:31], v[192:195], v[200:203], v[28:31]
	v_mfma_f32_16x16x32_bf16 v[56:59], v[184:187], v[208:211], v[56:59]
	v_mfma_f32_16x16x32_bf16 v[24:27], v[192:195], v[208:211], v[24:27]
	v_mfma_f32_16x16x32_bf16 v[52:55], v[184:187], v[216:219], v[52:55]
	v_mfma_f32_16x16x32_bf16 v[20:23], v[192:195], v[216:219], v[20:23]
	v_mfma_f32_16x16x32_bf16 v[48:51], v[184:187], v[236:239], v[48:51]
	v_mfma_f32_16x16x32_bf16 v[16:19], v[192:195], v[236:239], v[16:19]
	v_mfma_f32_16x16x32_bf16 v[60:63], v[188:191], v[204:207], v[60:63]
	v_mfma_f32_16x16x32_bf16 v[28:31], v[196:199], v[204:207], v[28:31]
	v_mfma_f32_16x16x32_bf16 v[56:59], v[188:191], v[212:215], v[56:59]
	v_mfma_f32_16x16x32_bf16 v[24:27], v[196:199], v[212:215], v[24:27]
	v_mfma_f32_16x16x32_bf16 v[52:55], v[188:191], v[232:235], v[52:55]
	v_mfma_f32_16x16x32_bf16 v[20:23], v[196:199], v[232:235], v[20:23]
	v_mfma_f32_16x16x32_bf16 v[48:51], v[188:191], v[240:243], v[48:51]
	v_mfma_f32_16x16x32_bf16 v[16:19], v[196:199], v[240:243], v[16:19]
	s_setprio 0
	s_barrier
	s_add_i32 s28, s28, s67
	s_mov_b32 m0, s28
	ds_read_b128 v[200:203], v231 offset:16384
	ds_read_b128 v[204:207], v231 offset:17408
	ds_read_b128 v[208:211], v231 offset:18432
	ds_read_b128 v[212:215], v231 offset:19456
	ds_read_b128 v[216:219], v231 offset:20480
	ds_read_b128 v[232:235], v231 offset:21504
	ds_read_b128 v[236:239], v231 offset:22528
	ds_read_b128 v[240:243], v231 offset:23552
	global_load_lds_dwordx4 v142, s[62:63]
	s_add_u32 s98, s62, 0x80
	s_addc_u32 s99, s63, 0
	s_add_i32 m0, s28, 0x2000
	s_add_u32 s28, s62, 0xb0000
	s_addc_u32 s29, s63, 0
	s_add_i32 s60, s79, s67
	global_load_lds_dwordx4 v156, s[62:63]
	s_mov_b32 m0, s60
	s_nop 0
	global_load_lds_dwordx4 v142, s[28:29]
	s_add_i32 m0, s60, 0x2000
	s_nop 0
	global_load_lds_dwordx4 v156, s[28:29]
	s_mov_b32 m0, s68
	s_nop 0
	global_load_lds_dwordx4 v142, s[64:65]
	s_add_u32 s100, s64, 0x80
	s_addc_u32 s101, s65, 0
	s_mov_b32 m0, s69
	s_nop 0
	global_load_lds_dwordx4 v156, s[64:65]
	s_waitcnt vmcnt(8)
	s_waitcnt lgkmcnt(0)
	s_barrier
	s_setprio 1
	s_waitcnt lgkmcnt(0)
	v_mfma_f32_16x16x32_bf16 v[112:115], v[108:111], v[200:203], v[114:117]
	v_mfma_f32_16x16x32_bf16 v[76:79], v[134:137], v[200:203], v[76:79]
	v_mfma_f32_16x16x32_bf16 v[104:107], v[108:111], v[208:211], v[104:107]
	v_mfma_f32_16x16x32_bf16 v[72:75], v[134:137], v[208:211], v[72:75]
	v_mfma_f32_16x16x32_bf16 v[100:103], v[108:111], v[216:219], v[100:103]
	v_mfma_f32_16x16x32_bf16 v[68:71], v[134:137], v[216:219], v[68:71]
	v_mfma_f32_16x16x32_bf16 v[96:99], v[108:111], v[236:239], v[96:99]
	v_mfma_f32_16x16x32_bf16 v[64:67], v[134:137], v[236:239], v[64:67]
	v_mfma_f32_16x16x32_bf16 v[112:115], v[130:133], v[204:207], v[112:115]
	v_mfma_f32_16x16x32_bf16 v[76:79], v[180:183], v[204:207], v[76:79]
	v_mfma_f32_16x16x32_bf16 v[104:107], v[130:133], v[212:215], v[104:107]
	v_mfma_f32_16x16x32_bf16 v[72:75], v[180:183], v[212:215], v[72:75]
	v_mfma_f32_16x16x32_bf16 v[100:103], v[130:133], v[232:235], v[100:103]
	v_mfma_f32_16x16x32_bf16 v[68:71], v[180:183], v[232:235], v[68:71]
	v_mfma_f32_16x16x32_bf16 v[96:99], v[130:133], v[240:243], v[96:99]
	v_mfma_f32_16x16x32_bf16 v[64:67], v[180:183], v[240:243], v[64:67]
	v_mfma_f32_16x16x32_bf16 v[44:47], v[184:187], v[200:203], v[44:47]
	v_mfma_f32_16x16x32_bf16 v[12:15], v[192:195], v[200:203], v[12:15]
	v_mfma_f32_16x16x32_bf16 v[40:43], v[184:187], v[208:211], v[40:43]
	v_mfma_f32_16x16x32_bf16 v[8:11], v[192:195], v[208:211], v[8:11]
	v_mfma_f32_16x16x32_bf16 v[36:39], v[184:187], v[216:219], v[36:39]
	v_mfma_f32_16x16x32_bf16 v[4:7], v[192:195], v[216:219], v[4:7]
	v_mfma_f32_16x16x32_bf16 v[32:35], v[184:187], v[236:239], v[32:35]
	v_mfma_f32_16x16x32_bf16 v[0:3], v[192:195], v[236:239], v[0:3]
	v_mfma_f32_16x16x32_bf16 v[44:47], v[188:191], v[204:207], v[44:47]
	v_mfma_f32_16x16x32_bf16 v[12:15], v[196:199], v[204:207], v[12:15]
	v_mfma_f32_16x16x32_bf16 v[40:43], v[188:191], v[212:215], v[40:43]
	v_mfma_f32_16x16x32_bf16 v[8:11], v[196:199], v[212:215], v[8:11]
	v_mfma_f32_16x16x32_bf16 v[36:39], v[188:191], v[232:235], v[36:39]
	v_mfma_f32_16x16x32_bf16 v[4:7], v[196:199], v[232:235], v[4:7]
	v_mfma_f32_16x16x32_bf16 v[32:35], v[188:191], v[240:243], v[32:35]
	v_mfma_f32_16x16x32_bf16 v[0:3], v[196:199], v[240:243], v[0:3]
	s_setprio 0
	s_barrier
	s_add_i32 s60, 0, 0x18000
	s_add_i32 s61, 0, 0x1c000
	ds_read_b128 v[108:111], v254 offset:32768
	ds_read_b128 v[130:133], v254 offset:33792
	ds_read_b128 v[134:137], v254 offset:34816
	ds_read_b128 v[180:183], v254 offset:35840
	ds_read_b128 v[184:187], v254 offset:49152
	ds_read_b128 v[188:191], v254 offset:50176
	ds_read_b128 v[192:195], v254 offset:51200
	ds_read_b128 v[196:199], v254 offset:52224
	s_add_u32 s28, s64, 0xb0000
	s_addc_u32 s29, s65, 0
	s_mov_b32 m0, s70
	ds_read_b128 v[200:203], v231 offset:32768
	ds_read_b128 v[204:207], v231 offset:33792
	ds_read_b128 v[208:211], v231 offset:34816
	ds_read_b128 v[212:215], v231 offset:35840
	ds_read_b128 v[216:219], v231 offset:36864
	ds_read_b128 v[232:235], v231 offset:37888
	ds_read_b128 v[236:239], v231 offset:38912
	ds_read_b128 v[240:243], v231 offset:39936
	global_load_lds_dwordx4 v142, s[28:29]
	s_mov_b32 m0, s71
	s_nop 0
	global_load_lds_dwordx4 v156, s[28:29]
	s_waitcnt vmcnt(8)
	s_waitcnt lgkmcnt(0)
	s_barrier
	s_setprio 1
	s_waitcnt lgkmcnt(0)
	v_mfma_f32_16x16x32_bf16 v[138:141], v[108:111], v[200:203], v[138:141]
	v_mfma_f32_16x16x32_bf16 v[92:95], v[134:137], v[200:203], v[92:95]
	v_mfma_f32_16x16x32_bf16 v[126:129], v[108:111], v[208:211], v[126:129]
	v_mfma_f32_16x16x32_bf16 v[88:91], v[134:137], v[208:211], v[88:91]
	v_mfma_f32_16x16x32_bf16 v[122:125], v[108:111], v[216:219], v[122:125]
	v_mfma_f32_16x16x32_bf16 v[84:87], v[134:137], v[216:219], v[84:87]
	v_mfma_f32_16x16x32_bf16 v[116:119], v[108:111], v[236:239], v[118:121]
	v_mfma_f32_16x16x32_bf16 v[80:83], v[134:137], v[236:239], v[80:83]
	v_mfma_f32_16x16x32_bf16 v[138:141], v[130:133], v[204:207], v[138:141]
	v_mfma_f32_16x16x32_bf16 v[92:95], v[180:183], v[204:207], v[92:95]
	v_mfma_f32_16x16x32_bf16 v[126:129], v[130:133], v[212:215], v[126:129]
	v_mfma_f32_16x16x32_bf16 v[88:91], v[180:183], v[212:215], v[88:91]
	v_mfma_f32_16x16x32_bf16 v[122:125], v[130:133], v[232:235], v[122:125]
	v_mfma_f32_16x16x32_bf16 v[84:87], v[180:183], v[232:235], v[84:87]
	v_mfma_f32_16x16x32_bf16 v[118:121], v[130:133], v[240:243], v[116:119]
	v_mfma_f32_16x16x32_bf16 v[80:83], v[180:183], v[240:243], v[80:83]
	v_mfma_f32_16x16x32_bf16 v[60:63], v[184:187], v[200:203], v[60:63]
	v_mfma_f32_16x16x32_bf16 v[28:31], v[192:195], v[200:203], v[28:31]
	v_mfma_f32_16x16x32_bf16 v[56:59], v[184:187], v[208:211], v[56:59]
	v_mfma_f32_16x16x32_bf16 v[24:27], v[192:195], v[208:211], v[24:27]
	v_mfma_f32_16x16x32_bf16 v[52:55], v[184:187], v[216:219], v[52:55]
	v_mfma_f32_16x16x32_bf16 v[20:23], v[192:195], v[216:219], v[20:23]
	v_mfma_f32_16x16x32_bf16 v[48:51], v[184:187], v[236:239], v[48:51]
	v_mfma_f32_16x16x32_bf16 v[16:19], v[192:195], v[236:239], v[16:19]
	v_mfma_f32_16x16x32_bf16 v[60:63], v[188:191], v[204:207], v[60:63]
	v_mfma_f32_16x16x32_bf16 v[28:31], v[196:199], v[204:207], v[28:31]
	v_mfma_f32_16x16x32_bf16 v[56:59], v[188:191], v[212:215], v[56:59]
	v_mfma_f32_16x16x32_bf16 v[24:27], v[196:199], v[212:215], v[24:27]
	v_mfma_f32_16x16x32_bf16 v[52:55], v[188:191], v[232:235], v[52:55]
	v_mfma_f32_16x16x32_bf16 v[20:23], v[196:199], v[232:235], v[20:23]
	v_mfma_f32_16x16x32_bf16 v[48:51], v[188:191], v[240:243], v[48:51]
	v_mfma_f32_16x16x32_bf16 v[16:19], v[196:199], v[240:243], v[16:19]
	s_setprio 0
	s_barrier
	s_add_i32 s28, s60, s67
	s_mov_b32 m0, s28
	ds_read_b128 v[200:203], v231 offset:49152
	ds_read_b128 v[204:207], v231 offset:50176
	ds_read_b128 v[208:211], v231 offset:51200
	ds_read_b128 v[212:215], v231 offset:52224
	ds_read_b128 v[216:219], v231 offset:53248
	ds_read_b128 v[232:235], v231 offset:54272
	ds_read_b128 v[236:239], v231 offset:55296
	ds_read_b128 v[240:243], v231 offset:56320
	global_load_lds_dwordx4 v142, s[98:99]
	s_add_i32 m0, s28, 0x2000
	s_add_u32 s28, s62, 0xb0080
	s_addc_u32 s29, s63, 0
	s_add_i32 s60, s61, s67
	global_load_lds_dwordx4 v156, s[98:99]
	s_mov_b32 m0, s60
	s_nop 0
	global_load_lds_dwordx4 v142, s[28:29]
	s_add_i32 m0, s60, 0x2000
	s_nop 0
	global_load_lds_dwordx4 v156, s[28:29]
	s_mov_b32 m0, s74
	s_nop 0
	global_load_lds_dwordx4 v142, s[100:101]
	s_mov_b32 m0, s75
	s_nop 0
	global_load_lds_dwordx4 v156, s[100:101]
	s_waitcnt vmcnt(8)
	s_waitcnt lgkmcnt(0)
	s_barrier
	s_setprio 1
	s_waitcnt lgkmcnt(0)
	v_mfma_f32_16x16x32_bf16 v[112:115], v[108:111], v[200:203], v[112:115]
	v_mfma_f32_16x16x32_bf16 v[76:79], v[134:137], v[200:203], v[76:79]
	v_mfma_f32_16x16x32_bf16 v[104:107], v[108:111], v[208:211], v[104:107]
	v_mfma_f32_16x16x32_bf16 v[72:75], v[134:137], v[208:211], v[72:75]
	v_mfma_f32_16x16x32_bf16 v[100:103], v[108:111], v[216:219], v[100:103]
	v_mfma_f32_16x16x32_bf16 v[68:71], v[134:137], v[216:219], v[68:71]
	v_mfma_f32_16x16x32_bf16 v[96:99], v[108:111], v[236:239], v[96:99]
	v_mfma_f32_16x16x32_bf16 v[64:67], v[134:137], v[236:239], v[64:67]
	v_mfma_f32_16x16x32_bf16 v[114:117], v[130:133], v[204:207], v[112:115]
	v_mfma_f32_16x16x32_bf16 v[76:79], v[180:183], v[204:207], v[76:79]
	v_mfma_f32_16x16x32_bf16 v[104:107], v[130:133], v[212:215], v[104:107]
	v_mfma_f32_16x16x32_bf16 v[72:75], v[180:183], v[212:215], v[72:75]
	v_mfma_f32_16x16x32_bf16 v[100:103], v[130:133], v[232:235], v[100:103]
	v_mfma_f32_16x16x32_bf16 v[68:71], v[180:183], v[232:235], v[68:71]
	v_mfma_f32_16x16x32_bf16 v[96:99], v[130:133], v[240:243], v[96:99]
	v_mfma_f32_16x16x32_bf16 v[64:67], v[180:183], v[240:243], v[64:67]
	v_mfma_f32_16x16x32_bf16 v[44:47], v[184:187], v[200:203], v[44:47]
	v_mfma_f32_16x16x32_bf16 v[12:15], v[192:195], v[200:203], v[12:15]
	v_mfma_f32_16x16x32_bf16 v[40:43], v[184:187], v[208:211], v[40:43]
	v_mfma_f32_16x16x32_bf16 v[8:11], v[192:195], v[208:211], v[8:11]
	v_mfma_f32_16x16x32_bf16 v[36:39], v[184:187], v[216:219], v[36:39]
	v_mfma_f32_16x16x32_bf16 v[4:7], v[192:195], v[216:219], v[4:7]
	v_mfma_f32_16x16x32_bf16 v[32:35], v[184:187], v[236:239], v[32:35]
	v_mfma_f32_16x16x32_bf16 v[0:3], v[192:195], v[236:239], v[0:3]
	v_mfma_f32_16x16x32_bf16 v[44:47], v[188:191], v[204:207], v[44:47]
	v_mfma_f32_16x16x32_bf16 v[12:15], v[196:199], v[204:207], v[12:15]
	v_mfma_f32_16x16x32_bf16 v[40:43], v[188:191], v[212:215], v[40:43]
	v_mfma_f32_16x16x32_bf16 v[8:11], v[196:199], v[212:215], v[8:11]
	v_mfma_f32_16x16x32_bf16 v[36:39], v[188:191], v[232:235], v[36:39]
	v_mfma_f32_16x16x32_bf16 v[4:7], v[196:199], v[232:235], v[4:7]
	v_mfma_f32_16x16x32_bf16 v[32:35], v[188:191], v[240:243], v[32:35]
	v_mfma_f32_16x16x32_bf16 v[0:3], v[196:199], v[240:243], v[0:3]
	s_setprio 0
	s_barrier
	s_add_i32 s59, s59, 2
	s_add_u32 s36, s36, 0x100
	s_addc_u32 s37, s37, 0
	s_cmp_gt_u32 s59, 41
	s_mov_b64 s[60:61], s[40:41]
	s_cbranch_scc0 .LBB0_276
	s_and_b64 vcc, exec, s[52:53]
	s_cbranch_vccz .LBB0_279
	s_barrier

.LBB0_496:
	v_lshrrev_b32_e32 v16, 1, v6
	v_and_b32_e32 v16, 24, v16
	v_and_b32_e32 v7, 15, v6
	v_lshlrev_b32_e32 v17, 1, v16
	v_lshlrev_b32_e32 v6, 2, v6
	v_lshl_or_b32 v156, s28, 6, v7
	v_lshl_or_b32 v7, v7, 6, v17
	s_lshl_b32 s28, s28, 13
	v_and_b32_e32 v6, 32, v6
	v_readlane_b32 s54, v250, 8
	v_bitop3_b32 v17, v7, s28, v6 bitop3:0xde
	s_lshl_b32 s28, s36, 5
	v_readlane_b32 s55, v250, 9
	s_and_b32 s28, s28, 0x60
	v_mov_b32_e32 v129, v143
	v_lshl_add_u64 v[8:9], s[54:55], 0, v[142:143]
	v_readlane_b32 s40, v251, 51
	s_lshl_b32 s29, s28, 7
	v_lshl_add_u64 v[10:11], s[54:55], 0, v[128:129]
	v_mov_b32_e32 v133, v143
	v_readlane_b32 s41, v251, 52
	v_bitop3_b32 v157, v7, s29, v6 bitop3:0xde
	v_add_u32_e32 v254, 0x10000, v157
	s_add_i32 m0, s62, 0x18000
	v_lshl_add_u64 v[6:7], v[8:9], 0, s[22:23]
	v_lshl_add_u64 v[12:13], s[40:41], 0, v[132:133]
	v_mov_b32_e32 v131, v143
	s_waitcnt vmcnt(2)
	s_barrier
	global_load_lds_dwordx4 v[6:7], off
	v_lshl_add_u64 v[6:7], v[10:11], 0, s[22:23]
	s_add_i32 m0, s62, 0x1a000
	s_add_i32 s66, s62, 0x8000
	v_lshl_add_u64 v[14:15], s[40:41], 0, v[130:131]
	global_load_lds_dwordx4 v[6:7], off
	v_lshl_add_u64 v[6:7], v[12:13], 0, s[22:23]
	s_mov_b32 m0, s66
	s_add_i32 s67, s62, 0xa000
	v_readlane_b32 s4, v250, 10
	global_load_lds_dwordx4 v[6:7], off
	v_lshl_add_u64 v[6:7], v[14:15], 0, s[22:23]
	s_mov_b32 m0, s67
	v_readlane_b32 s5, v250, 11
	global_load_lds_dwordx4 v[6:7], off
	s_add_i32 m0, s62, 0x1c000
	v_lshl_add_u64 v[6:7], s[4:5], 0, v[142:143]
	global_load_lds_dwordx4 v[6:7], off
	v_lshl_add_u64 v[6:7], s[4:5], 0, v[128:129]
	s_add_i32 m0, s62, 0x1e000
	s_cmpk_lt_u32 s2, 0x100
	global_load_lds_dwordx4 v[6:7], off
	v_lshlrev_b32_e32 v6, 14, v4
	v_and_b32_e32 v6, 0xffff8000, v6
	v_lshl_add_u32 v3, v3, 11, v6
	v_and_b32_e32 v4, 1, v4
	v_lshl_or_b32 v3, v4, 6, v3
	v_lshl_add_u32 v134, v5, 1, v3
	v_lshlrev_b32_e32 v3, 14, v0
	v_and_b32_e32 v3, 0xffff8000, v3
	s_waitcnt vmcnt(6)
	v_lshl_add_u32 v1, v1, 11, v3
	v_and_b32_e32 v0, 1, v0
	v_lshl_or_b32 v0, v0, 6, v1
	v_readlane_b32 s4, v251, 45
	s_cselect_b64 s[44:45], -1, 0
	v_or_b32_e32 v158, s28, v16
	v_mov_b32_e32 v135, v143
	v_lshl_add_u32 v136, v2, 1, v0
	v_mov_b32_e32 v137, v143
	s_mov_b32 s68, 0
	v_add_u32_e32 v159, 0, v17
	v_readlane_b32 s36, v251, 26
	s_mov_b32 s2, s4
	s_barrier
	v_readlane_b32 s5, v251, 46
	s_branch .LBB0_499

.LBB0_502:
	s_add_u32 s28, s40, 0xfffc0080
	s_addc_u32 s29, s41, -1
	s_add_i32 s69, 0, 0x10000
	s_cmp_eq_u32 s61, 12
	s_cselect_b32 s57, s37, s29
	s_cselect_b32 s56, s49, s28
	s_cselect_b32 s55, s47, s60
	s_cselect_b32 s54, s58, s59
	s_add_i32 s70, 0, 0x14000
	ds_read_b128 v[138:141], v254
	ds_read_b128 v[160:163], v254 offset:1024
	ds_read_b128 v[164:167], v254 offset:2048
	ds_read_b128 v[168:171], v254 offset:3072
	ds_read_b128 v[172:175], v254 offset:16384
	ds_read_b128 v[176:179], v254 offset:17408
	ds_read_b128 v[180:183], v254 offset:18432
	ds_read_b128 v[184:187], v254 offset:19456
	s_add_i32 m0, s62, 0xc000
	ds_read_b128 v[188:191], v159
	ds_read_b128 v[192:195], v159 offset:1024
	ds_read_b128 v[196:199], v159 offset:2048
	ds_read_b128 v[200:203], v159 offset:3072
	ds_read_b128 v[204:207], v159 offset:4096
	ds_read_b128 v[208:211], v159 offset:5120
	ds_read_b128 v[212:215], v159 offset:6144
	ds_read_b128 v[216:219], v159 offset:7168
	global_load_lds_dwordx4 v134, s[40:41]
	s_add_i32 m0, s62, 0xe000
	s_nop 0
	global_load_lds_dwordx4 v136, s[40:41]
	s_waitcnt vmcnt(8)
	s_waitcnt lgkmcnt(0)
	s_barrier
	s_setprio 1
	s_waitcnt lgkmcnt(0)
	v_mfma_f32_16x16x32_bf16 v[124:127], v[138:141], v[188:191], v[124:127]
	v_mfma_f32_16x16x32_bf16 v[120:123], v[164:167], v[188:191], v[120:123]
	v_mfma_f32_16x16x32_bf16 v[108:111], v[138:141], v[196:199], v[108:111]
	v_mfma_f32_16x16x32_bf16 v[104:107], v[164:167], v[196:199], v[104:107]
	v_mfma_f32_16x16x32_bf16 v[92:95], v[138:141], v[204:207], v[92:95]
	v_mfma_f32_16x16x32_bf16 v[88:91], v[164:167], v[204:207], v[88:91]
	v_mfma_f32_16x16x32_bf16 v[76:79], v[138:141], v[212:215], v[76:79]
	v_mfma_f32_16x16x32_bf16 v[72:75], v[164:167], v[212:215], v[72:75]
	v_mfma_f32_16x16x32_bf16 v[124:127], v[160:163], v[192:195], v[124:127]
	v_mfma_f32_16x16x32_bf16 v[120:123], v[168:171], v[192:195], v[120:123]
	v_mfma_f32_16x16x32_bf16 v[108:111], v[160:163], v[200:203], v[108:111]
	v_mfma_f32_16x16x32_bf16 v[104:107], v[168:171], v[200:203], v[104:107]
	v_mfma_f32_16x16x32_bf16 v[92:95], v[160:163], v[208:211], v[92:95]
	v_mfma_f32_16x16x32_bf16 v[88:91], v[168:171], v[208:211], v[88:91]
	v_mfma_f32_16x16x32_bf16 v[76:79], v[160:163], v[216:219], v[76:79]
	v_mfma_f32_16x16x32_bf16 v[72:75], v[168:171], v[216:219], v[72:75]
	v_mfma_f32_16x16x32_bf16 v[116:119], v[172:175], v[188:191], v[116:119]
	v_mfma_f32_16x16x32_bf16 v[112:115], v[180:183], v[188:191], v[112:115]
	v_mfma_f32_16x16x32_bf16 v[100:103], v[172:175], v[196:199], v[100:103]
	v_mfma_f32_16x16x32_bf16 v[96:99], v[180:183], v[196:199], v[96:99]
	v_mfma_f32_16x16x32_bf16 v[84:87], v[172:175], v[204:207], v[84:87]
	v_mfma_f32_16x16x32_bf16 v[80:83], v[180:183], v[204:207], v[80:83]
	v_mfma_f32_16x16x32_bf16 v[68:71], v[172:175], v[212:215], v[68:71]
	v_mfma_f32_16x16x32_bf16 v[64:67], v[180:183], v[212:215], v[64:67]
	v_mfma_f32_16x16x32_bf16 v[116:119], v[176:179], v[192:195], v[116:119]
	v_mfma_f32_16x16x32_bf16 v[112:115], v[184:187], v[192:195], v[112:115]
	v_mfma_f32_16x16x32_bf16 v[100:103], v[176:179], v[200:203], v[100:103]
	v_mfma_f32_16x16x32_bf16 v[96:99], v[184:187], v[200:203], v[96:99]
	v_mfma_f32_16x16x32_bf16 v[84:87], v[176:179], v[208:211], v[84:87]
	v_mfma_f32_16x16x32_bf16 v[80:83], v[184:187], v[208:211], v[80:83]
	v_mfma_f32_16x16x32_bf16 v[68:71], v[176:179], v[216:219], v[68:71]
	v_mfma_f32_16x16x32_bf16 v[64:67], v[184:187], v[216:219], v[64:67]
	s_setprio 0
	s_barrier
	s_add_i32 s28, s69, s20
	s_mov_b32 m0, s28
	ds_read_b128 v[188:191], v159 offset:16384
	ds_read_b128 v[192:195], v159 offset:17408
	ds_read_b128 v[196:199], v159 offset:18432
	ds_read_b128 v[200:203], v159 offset:19456
	ds_read_b128 v[204:207], v159 offset:20480
	ds_read_b128 v[208:211], v159 offset:21504
	ds_read_b128 v[212:215], v159 offset:22528
	ds_read_b128 v[216:219], v159 offset:23552
	global_load_lds_dwordx4 v142, s[54:55]
	s_add_u32 s98, s54, 0x80
	s_addc_u32 s99, s55, 0
	s_add_i32 m0, s28, 0x2000
	s_add_u32 s28, s54, 0x40000
	s_addc_u32 s29, s55, 0
	s_add_i32 s69, s70, s20
	global_load_lds_dwordx4 v128, s[54:55]
	s_mov_b32 m0, s69
	s_nop 0
	global_load_lds_dwordx4 v142, s[28:29]
	s_add_i32 m0, s69, 0x2000
	s_nop 0
	global_load_lds_dwordx4 v128, s[28:29]
	s_mov_b32 m0, s62
	s_nop 0
	global_load_lds_dwordx4 v132, s[56:57]
	s_add_u32 s100, s56, 0x80
	s_addc_u32 s101, s57, 0
	s_mov_b32 m0, s63
	s_nop 0
	global_load_lds_dwordx4 v130, s[56:57]
	s_waitcnt vmcnt(8)
	s_waitcnt lgkmcnt(0)
	s_barrier
	s_setprio 1
	s_waitcnt lgkmcnt(0)
	v_mfma_f32_16x16x32_bf16 v[60:63], v[138:141], v[188:191], v[60:63]
	v_mfma_f32_16x16x32_bf16 v[56:59], v[164:167], v[188:191], v[56:59]
	v_mfma_f32_16x16x32_bf16 v[44:47], v[138:141], v[196:199], v[44:47]
	v_mfma_f32_16x16x32_bf16 v[40:43], v[164:167], v[196:199], v[40:43]
	v_mfma_f32_16x16x32_bf16 v[28:31], v[138:141], v[204:207], v[28:31]
	v_mfma_f32_16x16x32_bf16 v[24:27], v[164:167], v[204:207], v[24:27]
	v_mfma_f32_16x16x32_bf16 v[12:15], v[138:141], v[212:215], v[12:15]
	v_mfma_f32_16x16x32_bf16 v[8:11], v[164:167], v[212:215], v[8:11]
	v_mfma_f32_16x16x32_bf16 v[60:63], v[160:163], v[192:195], v[60:63]
	v_mfma_f32_16x16x32_bf16 v[56:59], v[168:171], v[192:195], v[56:59]
	v_mfma_f32_16x16x32_bf16 v[44:47], v[160:163], v[200:203], v[44:47]
	v_mfma_f32_16x16x32_bf16 v[40:43], v[168:171], v[200:203], v[40:43]
	v_mfma_f32_16x16x32_bf16 v[28:31], v[160:163], v[208:211], v[28:31]
	v_mfma_f32_16x16x32_bf16 v[24:27], v[168:171], v[208:211], v[24:27]
	v_mfma_f32_16x16x32_bf16 v[12:15], v[160:163], v[216:219], v[12:15]
	v_mfma_f32_16x16x32_bf16 v[8:11], v[168:171], v[216:219], v[8:11]
	v_mfma_f32_16x16x32_bf16 v[52:55], v[172:175], v[188:191], v[52:55]
	v_mfma_f32_16x16x32_bf16 v[48:51], v[180:183], v[188:191], v[48:51]
	v_mfma_f32_16x16x32_bf16 v[36:39], v[172:175], v[196:199], v[36:39]
	v_mfma_f32_16x16x32_bf16 v[32:35], v[180:183], v[196:199], v[32:35]
	v_mfma_f32_16x16x32_bf16 v[20:23], v[172:175], v[204:207], v[20:23]
	v_mfma_f32_16x16x32_bf16 v[16:19], v[180:183], v[204:207], v[16:19]
	v_mfma_f32_16x16x32_bf16 v[4:7], v[172:175], v[212:215], v[4:7]
	v_mfma_f32_16x16x32_bf16 v[0:3], v[180:183], v[212:215], v[0:3]
	v_mfma_f32_16x16x32_bf16 v[52:55], v[176:179], v[192:195], v[52:55]
	v_mfma_f32_16x16x32_bf16 v[48:51], v[184:187], v[192:195], v[48:51]
	v_mfma_f32_16x16x32_bf16 v[36:39], v[176:179], v[200:203], v[36:39]
	v_mfma_f32_16x16x32_bf16 v[32:35], v[184:187], v[200:203], v[32:35]
	v_mfma_f32_16x16x32_bf16 v[20:23], v[176:179], v[208:211], v[20:23]
	v_mfma_f32_16x16x32_bf16 v[16:19], v[184:187], v[208:211], v[16:19]
	v_mfma_f32_16x16x32_bf16 v[4:7], v[176:179], v[216:219], v[4:7]
	v_mfma_f32_16x16x32_bf16 v[0:3], v[184:187], v[216:219], v[0:3]
	s_setprio 0
	s_barrier
	s_add_i32 s69, 0, 0x18000
	s_add_i32 s70, 0, 0x1c000
	ds_read_b128 v[138:141], v254 offset:32768
	ds_read_b128 v[160:163], v254 offset:33792
	ds_read_b128 v[164:167], v254 offset:34816
	ds_read_b128 v[168:171], v254 offset:35840
	ds_read_b128 v[172:175], v254 offset:49152
	ds_read_b128 v[176:179], v254 offset:50176
	ds_read_b128 v[180:183], v254 offset:51200
	ds_read_b128 v[184:187], v254 offset:52224
	s_add_u32 s28, s56, 0x40000
	s_addc_u32 s29, s57, 0
	s_mov_b32 m0, s64
	ds_read_b128 v[188:191], v159 offset:32768
	ds_read_b128 v[192:195], v159 offset:33792
	ds_read_b128 v[196:199], v159 offset:34816
	ds_read_b128 v[200:203], v159 offset:35840
	ds_read_b128 v[204:207], v159 offset:36864
	ds_read_b128 v[208:211], v159 offset:37888
	ds_read_b128 v[212:215], v159 offset:38912
	ds_read_b128 v[216:219], v159 offset:39936
	global_load_lds_dwordx4 v132, s[28:29]
	s_mov_b32 m0, s65
	s_nop 0
	global_load_lds_dwordx4 v130, s[28:29]
	s_waitcnt vmcnt(8)
	s_waitcnt lgkmcnt(0)
	s_barrier
	s_setprio 1
	s_waitcnt lgkmcnt(0)
	v_mfma_f32_16x16x32_bf16 v[124:127], v[138:141], v[188:191], v[124:127]
	v_mfma_f32_16x16x32_bf16 v[120:123], v[164:167], v[188:191], v[120:123]
	v_mfma_f32_16x16x32_bf16 v[108:111], v[138:141], v[196:199], v[108:111]
	v_mfma_f32_16x16x32_bf16 v[104:107], v[164:167], v[196:199], v[104:107]
	v_mfma_f32_16x16x32_bf16 v[92:95], v[138:141], v[204:207], v[92:95]
	v_mfma_f32_16x16x32_bf16 v[88:91], v[164:167], v[204:207], v[88:91]
	v_mfma_f32_16x16x32_bf16 v[76:79], v[138:141], v[212:215], v[76:79]
	v_mfma_f32_16x16x32_bf16 v[72:75], v[164:167], v[212:215], v[72:75]
	v_mfma_f32_16x16x32_bf16 v[124:127], v[160:163], v[192:195], v[124:127]
	v_mfma_f32_16x16x32_bf16 v[120:123], v[168:171], v[192:195], v[120:123]
	v_mfma_f32_16x16x32_bf16 v[108:111], v[160:163], v[200:203], v[108:111]
	v_mfma_f32_16x16x32_bf16 v[104:107], v[168:171], v[200:203], v[104:107]
	v_mfma_f32_16x16x32_bf16 v[92:95], v[160:163], v[208:211], v[92:95]
	v_mfma_f32_16x16x32_bf16 v[88:91], v[168:171], v[208:211], v[88:91]
	v_mfma_f32_16x16x32_bf16 v[76:79], v[160:163], v[216:219], v[76:79]
	v_mfma_f32_16x16x32_bf16 v[72:75], v[168:171], v[216:219], v[72:75]
	v_mfma_f32_16x16x32_bf16 v[116:119], v[172:175], v[188:191], v[116:119]
	v_mfma_f32_16x16x32_bf16 v[112:115], v[180:183], v[188:191], v[112:115]
	v_mfma_f32_16x16x32_bf16 v[100:103], v[172:175], v[196:199], v[100:103]
	v_mfma_f32_16x16x32_bf16 v[96:99], v[180:183], v[196:199], v[96:99]
	v_mfma_f32_16x16x32_bf16 v[84:87], v[172:175], v[204:207], v[84:87]
	v_mfma_f32_16x16x32_bf16 v[80:83], v[180:183], v[204:207], v[80:83]
	v_mfma_f32_16x16x32_bf16 v[68:71], v[172:175], v[212:215], v[68:71]
	v_mfma_f32_16x16x32_bf16 v[64:67], v[180:183], v[212:215], v[64:67]
	v_mfma_f32_16x16x32_bf16 v[116:119], v[176:179], v[192:195], v[116:119]
	v_mfma_f32_16x16x32_bf16 v[112:115], v[184:187], v[192:195], v[112:115]
	v_mfma_f32_16x16x32_bf16 v[100:103], v[176:179], v[200:203], v[100:103]
	v_mfma_f32_16x16x32_bf16 v[96:99], v[184:187], v[200:203], v[96:99]
	v_mfma_f32_16x16x32_bf16 v[84:87], v[176:179], v[208:211], v[84:87]
	v_mfma_f32_16x16x32_bf16 v[80:83], v[184:187], v[208:211], v[80:83]
	v_mfma_f32_16x16x32_bf16 v[68:71], v[176:179], v[216:219], v[68:71]
	v_mfma_f32_16x16x32_bf16 v[64:67], v[184:187], v[216:219], v[64:67]
	s_setprio 0
	s_barrier
	s_add_i32 s28, s69, s20
	s_mov_b32 m0, s28
	ds_read_b128 v[188:191], v159 offset:49152
	ds_read_b128 v[192:195], v159 offset:50176
	ds_read_b128 v[196:199], v159 offset:51200
	ds_read_b128 v[200:203], v159 offset:52224
	ds_read_b128 v[204:207], v159 offset:53248
	ds_read_b128 v[208:211], v159 offset:54272
	ds_read_b128 v[212:215], v159 offset:55296
	ds_read_b128 v[216:219], v159 offset:56320
	global_load_lds_dwordx4 v142, s[98:99]
	s_add_i32 m0, s28, 0x2000
	s_add_u32 s28, s54, 0x40080
	s_addc_u32 s29, s55, 0
	s_add_i32 s54, s70, s20
	global_load_lds_dwordx4 v128, s[98:99]
	s_mov_b32 m0, s54
	s_nop 0
	global_load_lds_dwordx4 v142, s[28:29]
	s_add_i32 m0, s54, 0x2000
	s_nop 0
	global_load_lds_dwordx4 v128, s[28:29]
	s_mov_b32 m0, s66
	s_nop 0
	global_load_lds_dwordx4 v132, s[100:101]
	s_mov_b32 m0, s67
	s_nop 0
	global_load_lds_dwordx4 v130, s[100:101]
	s_waitcnt vmcnt(8)
	s_waitcnt lgkmcnt(0)
	s_barrier
	s_setprio 1
	s_waitcnt lgkmcnt(0)
	v_mfma_f32_16x16x32_bf16 v[60:63], v[138:141], v[188:191], v[60:63]
	v_mfma_f32_16x16x32_bf16 v[56:59], v[164:167], v[188:191], v[56:59]
	v_mfma_f32_16x16x32_bf16 v[44:47], v[138:141], v[196:199], v[44:47]
	v_mfma_f32_16x16x32_bf16 v[40:43], v[164:167], v[196:199], v[40:43]
	v_mfma_f32_16x16x32_bf16 v[28:31], v[138:141], v[204:207], v[28:31]
	v_mfma_f32_16x16x32_bf16 v[24:27], v[164:167], v[204:207], v[24:27]
	v_mfma_f32_16x16x32_bf16 v[12:15], v[138:141], v[212:215], v[12:15]
	v_mfma_f32_16x16x32_bf16 v[8:11], v[164:167], v[212:215], v[8:11]
	v_mfma_f32_16x16x32_bf16 v[60:63], v[160:163], v[192:195], v[60:63]
	v_mfma_f32_16x16x32_bf16 v[56:59], v[168:171], v[192:195], v[56:59]
	v_mfma_f32_16x16x32_bf16 v[44:47], v[160:163], v[200:203], v[44:47]
	v_mfma_f32_16x16x32_bf16 v[40:43], v[168:171], v[200:203], v[40:43]
	v_mfma_f32_16x16x32_bf16 v[28:31], v[160:163], v[208:211], v[28:31]
	v_mfma_f32_16x16x32_bf16 v[24:27], v[168:171], v[208:211], v[24:27]
	v_mfma_f32_16x16x32_bf16 v[12:15], v[160:163], v[216:219], v[12:15]
	v_mfma_f32_16x16x32_bf16 v[8:11], v[168:171], v[216:219], v[8:11]
	v_mfma_f32_16x16x32_bf16 v[52:55], v[172:175], v[188:191], v[52:55]
	v_mfma_f32_16x16x32_bf16 v[48:51], v[180:183], v[188:191], v[48:51]
	v_mfma_f32_16x16x32_bf16 v[36:39], v[172:175], v[196:199], v[36:39]
	v_mfma_f32_16x16x32_bf16 v[32:35], v[180:183], v[196:199], v[32:35]
	v_mfma_f32_16x16x32_bf16 v[20:23], v[172:175], v[204:207], v[20:23]
	v_mfma_f32_16x16x32_bf16 v[16:19], v[180:183], v[204:207], v[16:19]
	v_mfma_f32_16x16x32_bf16 v[4:7], v[172:175], v[212:215], v[4:7]
	v_mfma_f32_16x16x32_bf16 v[0:3], v[180:183], v[212:215], v[0:3]
	v_mfma_f32_16x16x32_bf16 v[52:55], v[176:179], v[192:195], v[52:55]
	v_mfma_f32_16x16x32_bf16 v[48:51], v[184:187], v[192:195], v[48:51]
	v_mfma_f32_16x16x32_bf16 v[36:39], v[176:179], v[200:203], v[36:39]
	v_mfma_f32_16x16x32_bf16 v[32:35], v[184:187], v[200:203], v[32:35]
	v_mfma_f32_16x16x32_bf16 v[20:23], v[176:179], v[208:211], v[20:23]
	v_mfma_f32_16x16x32_bf16 v[16:19], v[184:187], v[208:211], v[16:19]
	v_mfma_f32_16x16x32_bf16 v[4:7], v[176:179], v[216:219], v[4:7]
	v_mfma_f32_16x16x32_bf16 v[0:3], v[184:187], v[216:219], v[0:3]
	s_setprio 0
	s_barrier
	s_add_i32 s61, s61, 2
	s_add_u32 s40, s40, 0x100
	s_addc_u32 s41, s41, 0
	s_add_u32 s59, s59, 0x100
	s_addc_u32 s60, s60, 0
	s_cmp_gt_u32 s61, 13
	s_cbranch_scc0 .LBB0_502
	s_and_b64 vcc, exec, s[44:45]
	s_cbranch_vccz .LBB0_505
	s_barrier

.LBB0_889:
	v_lshrrev_b32_e32 v16, 1, v6
	v_and_b32_e32 v16, 24, v16
	v_and_b32_e32 v7, 15, v6
	v_lshlrev_b32_e32 v17, 1, v16
	v_lshlrev_b32_e32 v6, 2, v6
	v_lshl_or_b32 v166, s28, 6, v7
	v_lshl_or_b32 v7, v7, 6, v17
	s_lshl_b32 s28, s28, 13
	v_and_b32_e32 v6, 32, v6
	v_readlane_b32 s54, v251, 55
	v_bitop3_b32 v17, v7, s28, v6 bitop3:0xde
	s_lshl_b32 s28, s39, 5
	v_mov_b32_e32 v133, v143
	v_readlane_b32 s55, v251, 56
	s_and_b32 s28, s28, 0x60
	v_mov_b32_e32 v129, v143
	v_lshl_add_u64 v[8:9], s[54:55], 0, v[132:133]
	v_readlane_b32 s52, v251, 51
	s_lshl_b32 s29, s28, 7
	v_lshl_add_u64 v[10:11], s[54:55], 0, v[128:129]
	v_mov_b32_e32 v135, v143
	v_readlane_b32 s53, v251, 52
	v_bitop3_b32 v167, v7, s29, v6 bitop3:0xde
	v_add_u32_e32 v254, 0x10000, v167
	s_add_i32 m0, s20, 0x18000
	v_lshl_add_u64 v[6:7], v[8:9], 0, s[22:23]
	v_lshl_add_u64 v[12:13], s[52:53], 0, v[134:135]
	v_mov_b32_e32 v131, v143
	s_waitcnt vmcnt(2)
	s_barrier
	global_load_lds_dwordx4 v[6:7], off
	v_lshl_add_u64 v[6:7], v[10:11], 0, s[22:23]
	s_add_i32 m0, s20, 0x1a000
	s_add_i32 s59, s20, 0x8000
	v_lshl_add_u64 v[14:15], s[52:53], 0, v[130:131]
	global_load_lds_dwordx4 v[6:7], off
	v_lshl_add_u64 v[6:7], v[12:13], 0, s[22:23]
	s_mov_b32 m0, s59
	s_add_i32 s60, s20, 0xa000
	v_readlane_b32 s4, v251, 57
	global_load_lds_dwordx4 v[6:7], off
	v_lshl_add_u64 v[6:7], v[14:15], 0, s[22:23]
	s_mov_b32 m0, s60
	v_readlane_b32 s5, v251, 58
	global_load_lds_dwordx4 v[6:7], off
	s_add_i32 m0, s20, 0x1c000
	v_lshl_add_u64 v[6:7], s[4:5], 0, v[132:133]
	global_load_lds_dwordx4 v[6:7], off
	v_lshl_add_u64 v[6:7], s[4:5], 0, v[128:129]
	s_add_i32 m0, s20, 0x1e000
	v_or_b32_e32 v168, s28, v16
	global_load_lds_dwordx4 v[6:7], off
	v_lshlrev_b32_e32 v6, 14, v4
	v_and_b32_e32 v6, 0xffff8000, v6
	v_lshl_add_u32 v3, v3, 11, v6
	v_and_b32_e32 v4, 1, v4
	v_lshl_or_b32 v3, v4, 6, v3
	v_lshl_add_u32 v136, v5, 1, v3
	v_lshlrev_b32_e32 v3, 14, v0
	v_and_b32_e32 v3, 0xffff8000, v3
	s_waitcnt vmcnt(6)
	v_lshl_add_u32 v1, v1, 11, v3
	v_and_b32_e32 v0, 1, v0
	s_cmpk_lt_u32 s38, 0x100
	v_lshl_or_b32 v0, v0, 6, v1
	v_readlane_b32 s4, v251, 45
	v_or_b32_e32 v169, 0xfffff800, v168
	s_cselect_b64 s[42:43], -1, 0
	v_mov_b32_e32 v137, v143
	v_lshl_add_u32 v138, v2, 1, v0
	v_mov_b32_e32 v139, v143
	s_mov_b32 s61, 0
	v_add_u32_e32 v170, 0, v17
	v_readlane_b32 s62, v251, 26
	s_mov_b32 s63, s4
	s_mov_b64 s[6:7], 0x40000
	s_mov_b64 s[8:9], 0x48000
	s_barrier
	v_readlane_b32 s5, v251, 46
	s_branch .LBB0_892

.LBB0_895:
	s_add_u32 s28, s52, 0xfffc0080
	s_addc_u32 s29, s53, -1
	s_add_i32 s69, 0, 0x10000
	s_cmp_eq_u32 s68, 12
	s_cselect_b32 s57, s47, s29
	s_cselect_b32 s56, s64, s28
	s_cselect_b32 s55, s45, s67
	s_cselect_b32 s54, s65, s66
	s_add_i32 s70, 0, 0x14000
	ds_read_b128 v[156:159], v254
	ds_read_b128 v[160:163], v254 offset:1024
	ds_read_b128 v[172:175], v254 offset:2048
	ds_read_b128 v[176:179], v254 offset:3072
	ds_read_b128 v[180:183], v254 offset:16384
	ds_read_b128 v[184:187], v254 offset:17408
	ds_read_b128 v[188:191], v254 offset:18432
	ds_read_b128 v[192:195], v254 offset:19456
	s_add_i32 m0, s20, 0xc000
	ds_read_b128 v[196:199], v170
	ds_read_b128 v[200:203], v170 offset:1024
	ds_read_b128 v[204:207], v170 offset:2048
	ds_read_b128 v[208:211], v170 offset:3072
	ds_read_b128 v[212:215], v170 offset:4096
	ds_read_b128 v[216:219], v170 offset:5120
	ds_read_b128 v[230:233], v170 offset:6144
	ds_read_b128 v[234:237], v170 offset:7168
	global_load_lds_dwordx4 v136, s[52:53]
	s_add_i32 m0, s20, 0xe000
	s_nop 0
	global_load_lds_dwordx4 v138, s[52:53]
	s_waitcnt vmcnt(8)
	s_waitcnt lgkmcnt(0)
	s_barrier
	s_setprio 1
	s_waitcnt lgkmcnt(0)
	v_mfma_f32_16x16x32_bf16 v[124:127], v[156:159], v[196:199], v[124:127]
	v_mfma_f32_16x16x32_bf16 v[120:123], v[172:175], v[196:199], v[120:123]
	v_mfma_f32_16x16x32_bf16 v[108:111], v[156:159], v[204:207], v[108:111]
	v_mfma_f32_16x16x32_bf16 v[104:107], v[172:175], v[204:207], v[104:107]
	v_mfma_f32_16x16x32_bf16 v[92:95], v[156:159], v[212:215], v[92:95]
	v_mfma_f32_16x16x32_bf16 v[88:91], v[172:175], v[212:215], v[88:91]
	v_mfma_f32_16x16x32_bf16 v[76:79], v[156:159], v[230:233], v[76:79]
	v_mfma_f32_16x16x32_bf16 v[72:75], v[172:175], v[230:233], v[72:75]
	v_mfma_f32_16x16x32_bf16 v[124:127], v[160:163], v[200:203], v[124:127]
	v_mfma_f32_16x16x32_bf16 v[120:123], v[176:179], v[200:203], v[120:123]
	v_mfma_f32_16x16x32_bf16 v[108:111], v[160:163], v[208:211], v[108:111]
	v_mfma_f32_16x16x32_bf16 v[104:107], v[176:179], v[208:211], v[104:107]
	v_mfma_f32_16x16x32_bf16 v[92:95], v[160:163], v[216:219], v[92:95]
	v_mfma_f32_16x16x32_bf16 v[88:91], v[176:179], v[216:219], v[88:91]
	v_mfma_f32_16x16x32_bf16 v[76:79], v[160:163], v[234:237], v[76:79]
	v_mfma_f32_16x16x32_bf16 v[72:75], v[176:179], v[234:237], v[72:75]
	v_mfma_f32_16x16x32_bf16 v[116:119], v[180:183], v[196:199], v[116:119]
	v_mfma_f32_16x16x32_bf16 v[112:115], v[188:191], v[196:199], v[112:115]
	v_mfma_f32_16x16x32_bf16 v[100:103], v[180:183], v[204:207], v[100:103]
	v_mfma_f32_16x16x32_bf16 v[96:99], v[188:191], v[204:207], v[96:99]
	v_mfma_f32_16x16x32_bf16 v[84:87], v[180:183], v[212:215], v[84:87]
	v_mfma_f32_16x16x32_bf16 v[80:83], v[188:191], v[212:215], v[80:83]
	v_mfma_f32_16x16x32_bf16 v[68:71], v[180:183], v[230:233], v[68:71]
	v_mfma_f32_16x16x32_bf16 v[64:67], v[188:191], v[230:233], v[64:67]
	v_mfma_f32_16x16x32_bf16 v[116:119], v[184:187], v[200:203], v[116:119]
	v_mfma_f32_16x16x32_bf16 v[112:115], v[192:195], v[200:203], v[112:115]
	v_mfma_f32_16x16x32_bf16 v[100:103], v[184:187], v[208:211], v[100:103]
	v_mfma_f32_16x16x32_bf16 v[96:99], v[192:195], v[208:211], v[96:99]
	v_mfma_f32_16x16x32_bf16 v[84:87], v[184:187], v[216:219], v[84:87]
	v_mfma_f32_16x16x32_bf16 v[80:83], v[192:195], v[216:219], v[80:83]
	v_mfma_f32_16x16x32_bf16 v[68:71], v[184:187], v[234:237], v[68:71]
	v_mfma_f32_16x16x32_bf16 v[64:67], v[192:195], v[234:237], v[64:67]
	s_setprio 0
	s_barrier
	s_add_i32 s28, s69, s2
	s_mov_b32 m0, s28
	ds_read_b128 v[196:199], v170 offset:16384
	ds_read_b128 v[200:203], v170 offset:17408
	ds_read_b128 v[204:207], v170 offset:18432
	ds_read_b128 v[208:211], v170 offset:19456
	ds_read_b128 v[212:215], v170 offset:20480
	ds_read_b128 v[216:219], v170 offset:21504
	ds_read_b128 v[230:233], v170 offset:22528
	ds_read_b128 v[234:237], v170 offset:23552
	global_load_lds_dwordx4 v132, s[54:55]
	s_add_u32 s98, s54, 0x80
	s_addc_u32 s99, s55, 0
	s_add_i32 m0, s28, 0x2000
	s_add_u32 s28, s54, 0x40000
	s_addc_u32 s29, s55, 0
	s_add_i32 s69, s70, s2
	global_load_lds_dwordx4 v128, s[54:55]
	s_mov_b32 m0, s69
	s_nop 0
	global_load_lds_dwordx4 v132, s[28:29]
	s_add_i32 m0, s69, 0x2000
	s_nop 0
	global_load_lds_dwordx4 v128, s[28:29]
	s_mov_b32 m0, s20
	s_nop 0
	global_load_lds_dwordx4 v134, s[56:57]
	s_add_u32 s100, s56, 0x80
	s_addc_u32 s101, s57, 0
	s_mov_b32 m0, s36
	s_nop 0
	global_load_lds_dwordx4 v130, s[56:57]
	s_waitcnt vmcnt(8)
	s_waitcnt lgkmcnt(0)
	s_barrier
	s_setprio 1
	s_waitcnt lgkmcnt(0)
	v_mfma_f32_16x16x32_bf16 v[60:63], v[156:159], v[196:199], v[60:63]
	v_mfma_f32_16x16x32_bf16 v[56:59], v[172:175], v[196:199], v[56:59]
	v_mfma_f32_16x16x32_bf16 v[48:51], v[156:159], v[204:207], v[48:51]
	v_mfma_f32_16x16x32_bf16 v[40:43], v[172:175], v[204:207], v[40:43]
	v_mfma_f32_16x16x32_bf16 v[32:35], v[156:159], v[212:215], v[32:35]
	v_mfma_f32_16x16x32_bf16 v[24:27], v[172:175], v[212:215], v[24:27]
	v_mfma_f32_16x16x32_bf16 v[16:19], v[156:159], v[230:233], v[16:19]
	v_mfma_f32_16x16x32_bf16 v[8:11], v[172:175], v[230:233], v[8:11]
	v_mfma_f32_16x16x32_bf16 v[60:63], v[160:163], v[200:203], v[60:63]
	v_mfma_f32_16x16x32_bf16 v[56:59], v[176:179], v[200:203], v[56:59]
	v_mfma_f32_16x16x32_bf16 v[48:51], v[160:163], v[208:211], v[48:51]
	v_mfma_f32_16x16x32_bf16 v[40:43], v[176:179], v[208:211], v[40:43]
	v_mfma_f32_16x16x32_bf16 v[32:35], v[160:163], v[216:219], v[32:35]
	v_mfma_f32_16x16x32_bf16 v[24:27], v[176:179], v[216:219], v[24:27]
	v_mfma_f32_16x16x32_bf16 v[16:19], v[160:163], v[234:237], v[16:19]
	v_mfma_f32_16x16x32_bf16 v[8:11], v[176:179], v[234:237], v[8:11]
	v_mfma_f32_16x16x32_bf16 v[52:55], v[180:183], v[196:199], v[52:55]
	v_mfma_f32_16x16x32_bf16 v[44:47], v[188:191], v[196:199], v[44:47]
	v_mfma_f32_16x16x32_bf16 v[36:39], v[180:183], v[204:207], v[36:39]
	v_mfma_f32_16x16x32_bf16 v[28:31], v[188:191], v[204:207], v[28:31]
	v_mfma_f32_16x16x32_bf16 v[20:23], v[180:183], v[212:215], v[20:23]
	v_mfma_f32_16x16x32_bf16 v[12:15], v[188:191], v[212:215], v[12:15]
	v_mfma_f32_16x16x32_bf16 v[4:7], v[180:183], v[230:233], v[4:7]
	v_mfma_f32_16x16x32_bf16 v[0:3], v[188:191], v[230:233], v[0:3]
	v_mfma_f32_16x16x32_bf16 v[52:55], v[184:187], v[200:203], v[52:55]
	v_mfma_f32_16x16x32_bf16 v[44:47], v[192:195], v[200:203], v[44:47]
	v_mfma_f32_16x16x32_bf16 v[36:39], v[184:187], v[208:211], v[36:39]
	v_mfma_f32_16x16x32_bf16 v[28:31], v[192:195], v[208:211], v[28:31]
	v_mfma_f32_16x16x32_bf16 v[20:23], v[184:187], v[216:219], v[20:23]
	v_mfma_f32_16x16x32_bf16 v[12:15], v[192:195], v[216:219], v[12:15]
	v_mfma_f32_16x16x32_bf16 v[4:7], v[184:187], v[234:237], v[4:7]
	v_mfma_f32_16x16x32_bf16 v[0:3], v[192:195], v[234:237], v[0:3]
	s_setprio 0
	s_barrier
	s_add_i32 s69, 0, 0x18000
	s_add_i32 s70, 0, 0x1c000
	ds_read_b128 v[156:159], v254 offset:32768
	ds_read_b128 v[160:163], v254 offset:33792
	ds_read_b128 v[172:175], v254 offset:34816
	ds_read_b128 v[176:179], v254 offset:35840
	ds_read_b128 v[180:183], v254 offset:49152
	ds_read_b128 v[184:187], v254 offset:50176
	ds_read_b128 v[188:191], v254 offset:51200
	ds_read_b128 v[192:195], v254 offset:52224
	s_add_u32 s28, s56, 0x40000
	s_addc_u32 s29, s57, 0
	s_mov_b32 m0, s37
	ds_read_b128 v[196:199], v170 offset:32768
	ds_read_b128 v[200:203], v170 offset:33792
	ds_read_b128 v[204:207], v170 offset:34816
	ds_read_b128 v[208:211], v170 offset:35840
	ds_read_b128 v[212:215], v170 offset:36864
	ds_read_b128 v[216:219], v170 offset:37888
	ds_read_b128 v[230:233], v170 offset:38912
	ds_read_b128 v[234:237], v170 offset:39936
	global_load_lds_dwordx4 v134, s[28:29]
	s_mov_b32 m0, s58
	s_nop 0
	global_load_lds_dwordx4 v130, s[28:29]
	s_waitcnt vmcnt(8)
	s_waitcnt lgkmcnt(0)
	s_barrier
	s_setprio 1
	s_waitcnt lgkmcnt(0)
	v_mfma_f32_16x16x32_bf16 v[124:127], v[156:159], v[196:199], v[124:127]
	v_mfma_f32_16x16x32_bf16 v[120:123], v[172:175], v[196:199], v[120:123]
	v_mfma_f32_16x16x32_bf16 v[108:111], v[156:159], v[204:207], v[108:111]
	v_mfma_f32_16x16x32_bf16 v[104:107], v[172:175], v[204:207], v[104:107]
	v_mfma_f32_16x16x32_bf16 v[92:95], v[156:159], v[212:215], v[92:95]
	v_mfma_f32_16x16x32_bf16 v[88:91], v[172:175], v[212:215], v[88:91]
	v_mfma_f32_16x16x32_bf16 v[76:79], v[156:159], v[230:233], v[76:79]
	v_mfma_f32_16x16x32_bf16 v[72:75], v[172:175], v[230:233], v[72:75]
	v_mfma_f32_16x16x32_bf16 v[124:127], v[160:163], v[200:203], v[124:127]
	v_mfma_f32_16x16x32_bf16 v[120:123], v[176:179], v[200:203], v[120:123]
	v_mfma_f32_16x16x32_bf16 v[108:111], v[160:163], v[208:211], v[108:111]
	v_mfma_f32_16x16x32_bf16 v[104:107], v[176:179], v[208:211], v[104:107]
	v_mfma_f32_16x16x32_bf16 v[92:95], v[160:163], v[216:219], v[92:95]
	v_mfma_f32_16x16x32_bf16 v[88:91], v[176:179], v[216:219], v[88:91]
	v_mfma_f32_16x16x32_bf16 v[76:79], v[160:163], v[234:237], v[76:79]
	v_mfma_f32_16x16x32_bf16 v[72:75], v[176:179], v[234:237], v[72:75]
	v_mfma_f32_16x16x32_bf16 v[116:119], v[180:183], v[196:199], v[116:119]
	v_mfma_f32_16x16x32_bf16 v[112:115], v[188:191], v[196:199], v[112:115]
	v_mfma_f32_16x16x32_bf16 v[100:103], v[180:183], v[204:207], v[100:103]
	v_mfma_f32_16x16x32_bf16 v[96:99], v[188:191], v[204:207], v[96:99]
	v_mfma_f32_16x16x32_bf16 v[84:87], v[180:183], v[212:215], v[84:87]
	v_mfma_f32_16x16x32_bf16 v[80:83], v[188:191], v[212:215], v[80:83]
	v_mfma_f32_16x16x32_bf16 v[68:71], v[180:183], v[230:233], v[68:71]
	v_mfma_f32_16x16x32_bf16 v[64:67], v[188:191], v[230:233], v[64:67]
	v_mfma_f32_16x16x32_bf16 v[116:119], v[184:187], v[200:203], v[116:119]
	v_mfma_f32_16x16x32_bf16 v[112:115], v[192:195], v[200:203], v[112:115]
	v_mfma_f32_16x16x32_bf16 v[100:103], v[184:187], v[208:211], v[100:103]
	v_mfma_f32_16x16x32_bf16 v[96:99], v[192:195], v[208:211], v[96:99]
	v_mfma_f32_16x16x32_bf16 v[84:87], v[184:187], v[216:219], v[84:87]
	v_mfma_f32_16x16x32_bf16 v[80:83], v[192:195], v[216:219], v[80:83]
	v_mfma_f32_16x16x32_bf16 v[68:71], v[184:187], v[234:237], v[68:71]
	v_mfma_f32_16x16x32_bf16 v[64:67], v[192:195], v[234:237], v[64:67]
	s_setprio 0
	s_barrier
	s_add_i32 s28, s69, s2
	s_mov_b32 m0, s28
	ds_read_b128 v[196:199], v170 offset:49152
	ds_read_b128 v[200:203], v170 offset:50176
	ds_read_b128 v[204:207], v170 offset:51200
	ds_read_b128 v[208:211], v170 offset:52224
	ds_read_b128 v[212:215], v170 offset:53248
	ds_read_b128 v[216:219], v170 offset:54272
	ds_read_b128 v[230:233], v170 offset:55296
	ds_read_b128 v[234:237], v170 offset:56320
	global_load_lds_dwordx4 v132, s[98:99]
	s_add_i32 m0, s28, 0x2000
	s_add_u32 s28, s54, 0x40080
	s_addc_u32 s29, s55, 0
	s_add_i32 s54, s70, s2
	global_load_lds_dwordx4 v128, s[98:99]
	s_mov_b32 m0, s54
	s_nop 0
	global_load_lds_dwordx4 v132, s[28:29]
	s_add_i32 m0, s54, 0x2000
	s_nop 0
	global_load_lds_dwordx4 v128, s[28:29]
	s_mov_b32 m0, s59
	s_nop 0
	global_load_lds_dwordx4 v134, s[100:101]
	s_mov_b32 m0, s60
	s_nop 0
	global_load_lds_dwordx4 v130, s[100:101]
	s_waitcnt vmcnt(8)
	s_waitcnt lgkmcnt(0)
	s_barrier
	s_setprio 1
	s_waitcnt lgkmcnt(0)
	v_mfma_f32_16x16x32_bf16 v[60:63], v[156:159], v[196:199], v[60:63]
	v_mfma_f32_16x16x32_bf16 v[56:59], v[172:175], v[196:199], v[56:59]
	v_mfma_f32_16x16x32_bf16 v[48:51], v[156:159], v[204:207], v[48:51]
	v_mfma_f32_16x16x32_bf16 v[40:43], v[172:175], v[204:207], v[40:43]
	v_mfma_f32_16x16x32_bf16 v[32:35], v[156:159], v[212:215], v[32:35]
	v_mfma_f32_16x16x32_bf16 v[24:27], v[172:175], v[212:215], v[24:27]
	v_mfma_f32_16x16x32_bf16 v[16:19], v[156:159], v[230:233], v[16:19]
	v_mfma_f32_16x16x32_bf16 v[8:11], v[172:175], v[230:233], v[8:11]
	v_mfma_f32_16x16x32_bf16 v[60:63], v[160:163], v[200:203], v[60:63]
	v_mfma_f32_16x16x32_bf16 v[56:59], v[176:179], v[200:203], v[56:59]
	v_mfma_f32_16x16x32_bf16 v[48:51], v[160:163], v[208:211], v[48:51]
	v_mfma_f32_16x16x32_bf16 v[40:43], v[176:179], v[208:211], v[40:43]
	v_mfma_f32_16x16x32_bf16 v[32:35], v[160:163], v[216:219], v[32:35]
	v_mfma_f32_16x16x32_bf16 v[24:27], v[176:179], v[216:219], v[24:27]
	v_mfma_f32_16x16x32_bf16 v[16:19], v[160:163], v[234:237], v[16:19]
	v_mfma_f32_16x16x32_bf16 v[8:11], v[176:179], v[234:237], v[8:11]
	v_mfma_f32_16x16x32_bf16 v[52:55], v[180:183], v[196:199], v[52:55]
	v_mfma_f32_16x16x32_bf16 v[44:47], v[188:191], v[196:199], v[44:47]
	v_mfma_f32_16x16x32_bf16 v[36:39], v[180:183], v[204:207], v[36:39]
	v_mfma_f32_16x16x32_bf16 v[28:31], v[188:191], v[204:207], v[28:31]
	v_mfma_f32_16x16x32_bf16 v[20:23], v[180:183], v[212:215], v[20:23]
	v_mfma_f32_16x16x32_bf16 v[12:15], v[188:191], v[212:215], v[12:15]
	v_mfma_f32_16x16x32_bf16 v[4:7], v[180:183], v[230:233], v[4:7]
	v_mfma_f32_16x16x32_bf16 v[0:3], v[188:191], v[230:233], v[0:3]
	v_mfma_f32_16x16x32_bf16 v[52:55], v[184:187], v[200:203], v[52:55]
	v_mfma_f32_16x16x32_bf16 v[44:47], v[192:195], v[200:203], v[44:47]
	v_mfma_f32_16x16x32_bf16 v[36:39], v[184:187], v[208:211], v[36:39]
	v_mfma_f32_16x16x32_bf16 v[28:31], v[192:195], v[208:211], v[28:31]
	v_mfma_f32_16x16x32_bf16 v[20:23], v[184:187], v[216:219], v[20:23]
	v_mfma_f32_16x16x32_bf16 v[12:15], v[192:195], v[216:219], v[12:15]
	v_mfma_f32_16x16x32_bf16 v[4:7], v[184:187], v[234:237], v[4:7]
	v_mfma_f32_16x16x32_bf16 v[0:3], v[192:195], v[234:237], v[0:3]
	s_setprio 0
	s_barrier
	s_add_i32 s68, s68, 2
	s_add_u32 s52, s52, 0x100
	s_addc_u32 s53, s53, 0
	s_add_u32 s66, s66, 0x100
	s_addc_u32 s67, s67, 0
	s_cmp_gt_u32 s68, 13
	s_cbranch_scc0 .LBB0_895
	s_and_b64 vcc, exec, s[42:43]
	s_cbranch_vccz .LBB0_898
	s_barrier

.LBB0_1073:
	s_lshl_b32 s28, s50, 5
	s_and_b32 s52, s28, 0x60
	s_add_i32 m0, s20, 0x18000
	v_lshl_add_u64 v[6:7], v[6:7], 0, s[22:23]
	s_lshl_b32 s51, s37, 13
	s_lshl_b32 s50, s52, 7
	s_waitcnt vmcnt(2)
	s_barrier
	global_load_lds_dwordx4 v[6:7], off
	v_lshl_add_u64 v[4:5], v[4:5], 0, s[22:23]
	s_add_i32 m0, s20, 0x1a000
	s_add_i32 s72, s20, 0x8000
	s_add_i32 s73, s20, 0xa000
	global_load_lds_dwordx4 v[4:5], off
	v_lshl_add_u64 v[0:1], v[0:1], 0, s[22:23]
	s_mov_b32 m0, s72
	s_add_u32 s28, s64, 0x40080
	global_load_lds_dwordx4 v[0:1], off
	v_lshl_add_u64 v[0:1], v[2:3], 0, s[22:23]
	s_mov_b32 m0, s73
	s_addc_u32 s29, s65, 0
	global_load_lds_dwordx4 v[0:1], off
	s_add_i32 m0, s20, 0x1c000
	v_lshl_add_u64 v[0:1], s[28:29], 0, v[142:143]
	global_load_lds_dwordx4 v[0:1], off
	v_lshl_add_u64 v[0:1], s[28:29], 0, v[136:137]
	s_add_i32 m0, s20, 0x1e000
	v_bfe_u32 v6, v12, 4, 2
	global_load_lds_dwordx4 v[0:1], off
	v_and_b32_e32 v0, 15, v12
	v_lshlrev_b32_e32 v1, 4, v6
	v_lshl_or_b32 v138, s37, 6, v0
	v_lshl_or_b32 v0, v0, 6, v1
	v_lshlrev_b32_e32 v1, 2, v12
	v_and_b32_e32 v1, 32, v1
	v_bitop3_b32 v7, v0, s51, v1 bitop3:0xde
	v_bitop3_b32 v198, v0, s50, v1 bitop3:0xde
	v_add_u32_e32 v254, 0x10000, v198
	v_or_b32_e32 v0, 16, v138
	v_ashrrev_i32_e32 v1, 31, v0
	v_lshlrev_b64 v[164:165], 12, v[0:1]
	v_lshlrev_b32_e32 v0, 13, v14
	v_and_b32_e32 v0, 0x7fffc000, v0
	v_lshl_add_u32 v0, v13, 10, v0
	v_or_b32_e32 v0, v0, v15
	v_add_lshl_u32 v0, v0, v16, 1
	v_mov_b32_e32 v1, v143
	s_mov_b64 s[4:5], 0x40080
	v_ashrrev_i32_e32 v139, 31, v138
	v_lshl_add_u64 v[170:171], v[0:1], 0, s[4:5]
	v_lshlrev_b32_e32 v0, 13, v8
	v_lshlrev_b64 v[140:141], 12, v[138:139]
	s_mov_b64 s[28:29], 0x80000
	v_and_b32_e32 v0, 0x7fffc000, v0
	v_lshl_add_u64 v[156:157], v[140:141], 0, s[28:29]
	s_mov_b64 s[28:29], 0x90000
	v_lshl_add_u32 v0, v9, 10, v0
	s_waitcnt vmcnt(6)
	v_or_b32_e32 v2, 32, v138
	v_or_b32_e32 v4, 48, v138
	v_lshl_add_u64 v[158:159], v[140:141], 0, s[28:29]
	s_mov_b64 s[28:29], 0xa0000
	v_or_b32_e32 v0, v0, v10
	s_cmpk_lt_u32 s36, 0x100
	v_ashrrev_i32_e32 v3, 31, v2
	v_ashrrev_i32_e32 v5, 31, v4
	v_lshl_add_u64 v[160:161], v[140:141], 0, s[28:29]
	s_mov_b64 s[28:29], 0xb0000
	v_add_lshl_u32 v0, v0, v11, 1
	s_cselect_b64 s[50:51], -1, 0
	v_lshl_add_u64 v[162:163], v[140:141], 0, s[28:29]
	v_lshlrev_b64 v[166:167], 12, v[2:3]
	v_lshlrev_b64 v[168:169], 12, v[4:5]
	v_lshl_or_b32 v139, v6, 2, s52
	v_lshl_add_u64 v[172:173], v[0:1], 0, s[4:5]
	s_mov_b32 s74, 0
	v_add_u32_e32 v199, 0, v7
	v_readlane_b32 s75, v250, 12
	v_readlane_b32 s60, v250, 15
	s_barrier
	v_readlane_b32 s61, v250, 16
	s_branch .LBB0_1076

.LBB0_1083:
	s_add_u32 s64, s62, 0x100
	s_addc_u32 s65, s63, 0
	s_add_i32 s28, 0, 0x10000
	s_cmp_eq_u32 s79, 12
	s_cselect_b32 s69, s55, s65
	s_cselect_b32 s68, s61, s64
	s_cselect_b32 s67, s53, s78
	s_cselect_b32 s66, s76, s77
	s_add_i32 s80, 0, 0x14000
	ds_read_b128 v[124:127], v254
	ds_read_b128 v[128:131], v254 offset:1024
	ds_read_b128 v[174:177], v254 offset:2048
	ds_read_b128 v[178:181], v254 offset:3072
	ds_read_b128 v[182:185], v254 offset:16384
	ds_read_b128 v[186:189], v254 offset:17408
	ds_read_b128 v[190:193], v254 offset:18432
	ds_read_b128 v[194:197], v254 offset:19456
	s_add_i32 m0, s20, 0xc000
	ds_read_b128 v[200:203], v199
	ds_read_b128 v[204:207], v199 offset:1024
	ds_read_b128 v[208:211], v199 offset:2048
	ds_read_b128 v[212:215], v199 offset:3072
	ds_read_b128 v[216:219], v199 offset:4096
	ds_read_b128 v[230:233], v199 offset:5120
	ds_read_b128 v[234:237], v199 offset:6144
	ds_read_b128 v[238:241], v199 offset:7168
	global_load_lds_dwordx4 v170, s[62:63]
	s_add_i32 m0, s20, 0xe000
	s_nop 0
	global_load_lds_dwordx4 v172, s[62:63]
	s_waitcnt vmcnt(8)
	s_waitcnt lgkmcnt(0)
	s_barrier
	s_setprio 1
	s_waitcnt lgkmcnt(0)
	v_mfma_f32_16x16x32_bf16 v[132:135], v[124:127], v[200:203], v[132:135]
	v_mfma_f32_16x16x32_bf16 v[96:99], v[174:177], v[200:203], v[96:99]
	v_mfma_f32_16x16x32_bf16 v[120:123], v[124:127], v[208:211], v[120:123]
	v_mfma_f32_16x16x32_bf16 v[88:91], v[174:177], v[208:211], v[88:91]
	v_mfma_f32_16x16x32_bf16 v[116:119], v[124:127], v[216:219], v[116:119]
	v_mfma_f32_16x16x32_bf16 v[84:87], v[174:177], v[216:219], v[84:87]
	v_mfma_f32_16x16x32_bf16 v[112:115], v[124:127], v[234:237], v[112:115]
	v_mfma_f32_16x16x32_bf16 v[80:83], v[174:177], v[234:237], v[80:83]
	v_mfma_f32_16x16x32_bf16 v[132:135], v[128:131], v[204:207], v[132:135]
	v_mfma_f32_16x16x32_bf16 v[96:99], v[178:181], v[204:207], v[96:99]
	v_mfma_f32_16x16x32_bf16 v[120:123], v[128:131], v[212:215], v[120:123]
	v_mfma_f32_16x16x32_bf16 v[88:91], v[178:181], v[212:215], v[88:91]
	v_mfma_f32_16x16x32_bf16 v[116:119], v[128:131], v[230:233], v[116:119]
	v_mfma_f32_16x16x32_bf16 v[84:87], v[178:181], v[230:233], v[84:87]
	v_mfma_f32_16x16x32_bf16 v[112:115], v[128:131], v[238:241], v[112:115]
	v_mfma_f32_16x16x32_bf16 v[80:83], v[178:181], v[238:241], v[80:83]
	v_mfma_f32_16x16x32_bf16 v[64:67], v[182:185], v[200:203], v[64:67]
	v_mfma_f32_16x16x32_bf16 v[32:35], v[190:193], v[200:203], v[32:35]
	v_mfma_f32_16x16x32_bf16 v[56:59], v[182:185], v[208:211], v[56:59]
	v_mfma_f32_16x16x32_bf16 v[24:27], v[190:193], v[208:211], v[24:27]
	v_mfma_f32_16x16x32_bf16 v[52:55], v[182:185], v[216:219], v[52:55]
	v_mfma_f32_16x16x32_bf16 v[20:23], v[190:193], v[216:219], v[20:23]
	v_mfma_f32_16x16x32_bf16 v[48:51], v[182:185], v[234:237], v[48:51]
	v_mfma_f32_16x16x32_bf16 v[16:19], v[190:193], v[234:237], v[16:19]
	v_mfma_f32_16x16x32_bf16 v[64:67], v[186:189], v[204:207], v[64:67]
	v_mfma_f32_16x16x32_bf16 v[32:35], v[194:197], v[204:207], v[32:35]
	v_mfma_f32_16x16x32_bf16 v[56:59], v[186:189], v[212:215], v[56:59]
	v_mfma_f32_16x16x32_bf16 v[24:27], v[194:197], v[212:215], v[24:27]
	v_mfma_f32_16x16x32_bf16 v[52:55], v[186:189], v[230:233], v[52:55]
	v_mfma_f32_16x16x32_bf16 v[20:23], v[194:197], v[230:233], v[20:23]
	v_mfma_f32_16x16x32_bf16 v[48:51], v[186:189], v[238:241], v[48:51]
	v_mfma_f32_16x16x32_bf16 v[16:19], v[194:197], v[238:241], v[16:19]
	s_setprio 0
	s_barrier
	s_add_i32 s28, s28, s2
	s_mov_b32 m0, s28
	ds_read_b128 v[200:203], v199 offset:16384
	ds_read_b128 v[204:207], v199 offset:17408
	ds_read_b128 v[208:211], v199 offset:18432
	ds_read_b128 v[212:215], v199 offset:19456
	ds_read_b128 v[216:219], v199 offset:20480
	ds_read_b128 v[230:233], v199 offset:21504
	ds_read_b128 v[234:237], v199 offset:22528
	ds_read_b128 v[238:241], v199 offset:23552
	global_load_lds_dwordx4 v142, s[66:67]
	s_add_u32 s98, s66, 0x80
	s_addc_u32 s99, s67, 0
	s_add_i32 m0, s28, 0x2000
	s_add_u32 s28, s66, 0x40000
	s_addc_u32 s29, s67, 0
	s_add_i32 s62, s80, s2
	global_load_lds_dwordx4 v136, s[66:67]
	s_mov_b32 m0, s62
	s_nop 0
	global_load_lds_dwordx4 v142, s[28:29]
	s_add_i32 m0, s62, 0x2000
	s_nop 0
	global_load_lds_dwordx4 v136, s[28:29]
	s_mov_b32 m0, s20
	s_nop 0
	global_load_lds_dwordx4 v142, s[68:69]
	s_add_u32 s100, s68, 0x80
	s_addc_u32 s101, s69, 0
	s_mov_b32 m0, s39
	s_nop 0
	global_load_lds_dwordx4 v136, s[68:69]
	s_waitcnt vmcnt(8)
	s_waitcnt lgkmcnt(0)
	s_barrier
	s_setprio 1
	s_waitcnt lgkmcnt(0)
	v_mfma_f32_16x16x32_bf16 v[108:111], v[124:127], v[200:203], v[108:111]
	v_mfma_f32_16x16x32_bf16 v[76:79], v[174:177], v[200:203], v[76:79]
	v_mfma_f32_16x16x32_bf16 v[104:107], v[124:127], v[208:211], v[104:107]
	v_mfma_f32_16x16x32_bf16 v[72:75], v[174:177], v[208:211], v[72:75]
	v_mfma_f32_16x16x32_bf16 v[100:103], v[124:127], v[216:219], v[100:103]
	v_mfma_f32_16x16x32_bf16 v[68:71], v[174:177], v[216:219], v[68:71]
	v_mfma_f32_16x16x32_bf16 v[92:95], v[124:127], v[234:237], v[92:95]
	v_mfma_f32_16x16x32_bf16 v[60:63], v[174:177], v[234:237], v[60:63]
	v_mfma_f32_16x16x32_bf16 v[108:111], v[128:131], v[204:207], v[108:111]
	v_mfma_f32_16x16x32_bf16 v[76:79], v[178:181], v[204:207], v[76:79]
	v_mfma_f32_16x16x32_bf16 v[104:107], v[128:131], v[212:215], v[104:107]
	v_mfma_f32_16x16x32_bf16 v[72:75], v[178:181], v[212:215], v[72:75]
	v_mfma_f32_16x16x32_bf16 v[100:103], v[128:131], v[230:233], v[100:103]
	v_mfma_f32_16x16x32_bf16 v[68:71], v[178:181], v[230:233], v[68:71]
	v_mfma_f32_16x16x32_bf16 v[92:95], v[128:131], v[238:241], v[92:95]
	v_mfma_f32_16x16x32_bf16 v[60:63], v[178:181], v[238:241], v[60:63]
	v_mfma_f32_16x16x32_bf16 v[44:47], v[182:185], v[200:203], v[44:47]
	v_mfma_f32_16x16x32_bf16 v[12:15], v[190:193], v[200:203], v[12:15]
	v_mfma_f32_16x16x32_bf16 v[40:43], v[182:185], v[208:211], v[40:43]
	v_mfma_f32_16x16x32_bf16 v[8:11], v[190:193], v[208:211], v[8:11]
	v_mfma_f32_16x16x32_bf16 v[36:39], v[182:185], v[216:219], v[36:39]
	v_mfma_f32_16x16x32_bf16 v[4:7], v[190:193], v[216:219], v[4:7]
	v_mfma_f32_16x16x32_bf16 v[28:31], v[182:185], v[234:237], v[28:31]
	v_mfma_f32_16x16x32_bf16 v[0:3], v[190:193], v[234:237], v[0:3]
	v_mfma_f32_16x16x32_bf16 v[44:47], v[186:189], v[204:207], v[44:47]
	v_mfma_f32_16x16x32_bf16 v[12:15], v[194:197], v[204:207], v[12:15]
	v_mfma_f32_16x16x32_bf16 v[40:43], v[186:189], v[212:215], v[40:43]
	v_mfma_f32_16x16x32_bf16 v[8:11], v[194:197], v[212:215], v[8:11]
	v_mfma_f32_16x16x32_bf16 v[36:39], v[186:189], v[230:233], v[36:39]
	v_mfma_f32_16x16x32_bf16 v[4:7], v[194:197], v[230:233], v[4:7]
	v_mfma_f32_16x16x32_bf16 v[28:31], v[186:189], v[238:241], v[28:31]
	v_mfma_f32_16x16x32_bf16 v[0:3], v[194:197], v[238:241], v[0:3]
	s_setprio 0
	s_barrier
	s_add_i32 s62, 0, 0x18000
	s_add_i32 s63, 0, 0x1c000
	ds_read_b128 v[124:127], v254 offset:32768
	ds_read_b128 v[128:131], v254 offset:33792
	ds_read_b128 v[174:177], v254 offset:34816
	ds_read_b128 v[178:181], v254 offset:35840
	ds_read_b128 v[182:185], v254 offset:49152
	ds_read_b128 v[186:189], v254 offset:50176
	ds_read_b128 v[190:193], v254 offset:51200
	ds_read_b128 v[194:197], v254 offset:52224
	s_add_u32 s28, s68, 0x40000
	s_addc_u32 s29, s69, 0
	s_mov_b32 m0, s70
	ds_read_b128 v[200:203], v199 offset:32768
	ds_read_b128 v[204:207], v199 offset:33792
	ds_read_b128 v[208:211], v199 offset:34816
	ds_read_b128 v[212:215], v199 offset:35840
	ds_read_b128 v[216:219], v199 offset:36864
	ds_read_b128 v[230:233], v199 offset:37888
	ds_read_b128 v[234:237], v199 offset:38912
	ds_read_b128 v[238:241], v199 offset:39936
	global_load_lds_dwordx4 v142, s[28:29]
	s_mov_b32 m0, s71
	s_nop 0
	global_load_lds_dwordx4 v136, s[28:29]
	s_waitcnt vmcnt(8)
	s_waitcnt lgkmcnt(0)
	s_barrier
	s_setprio 1
	s_waitcnt lgkmcnt(0)
	v_mfma_f32_16x16x32_bf16 v[132:135], v[124:127], v[200:203], v[132:135]
	v_mfma_f32_16x16x32_bf16 v[96:99], v[174:177], v[200:203], v[96:99]
	v_mfma_f32_16x16x32_bf16 v[120:123], v[124:127], v[208:211], v[120:123]
	v_mfma_f32_16x16x32_bf16 v[88:91], v[174:177], v[208:211], v[88:91]
	v_mfma_f32_16x16x32_bf16 v[116:119], v[124:127], v[216:219], v[116:119]
	v_mfma_f32_16x16x32_bf16 v[84:87], v[174:177], v[216:219], v[84:87]
	v_mfma_f32_16x16x32_bf16 v[112:115], v[124:127], v[234:237], v[112:115]
	v_mfma_f32_16x16x32_bf16 v[80:83], v[174:177], v[234:237], v[80:83]
	v_mfma_f32_16x16x32_bf16 v[132:135], v[128:131], v[204:207], v[132:135]
	v_mfma_f32_16x16x32_bf16 v[96:99], v[178:181], v[204:207], v[96:99]
	v_mfma_f32_16x16x32_bf16 v[120:123], v[128:131], v[212:215], v[120:123]
	v_mfma_f32_16x16x32_bf16 v[88:91], v[178:181], v[212:215], v[88:91]
	v_mfma_f32_16x16x32_bf16 v[116:119], v[128:131], v[230:233], v[116:119]
	v_mfma_f32_16x16x32_bf16 v[84:87], v[178:181], v[230:233], v[84:87]
	v_mfma_f32_16x16x32_bf16 v[112:115], v[128:131], v[238:241], v[112:115]
	v_mfma_f32_16x16x32_bf16 v[80:83], v[178:181], v[238:241], v[80:83]
	v_mfma_f32_16x16x32_bf16 v[64:67], v[182:185], v[200:203], v[64:67]
	v_mfma_f32_16x16x32_bf16 v[32:35], v[190:193], v[200:203], v[32:35]
	v_mfma_f32_16x16x32_bf16 v[56:59], v[182:185], v[208:211], v[56:59]
	v_mfma_f32_16x16x32_bf16 v[24:27], v[190:193], v[208:211], v[24:27]
	v_mfma_f32_16x16x32_bf16 v[52:55], v[182:185], v[216:219], v[52:55]
	v_mfma_f32_16x16x32_bf16 v[20:23], v[190:193], v[216:219], v[20:23]
	v_mfma_f32_16x16x32_bf16 v[48:51], v[182:185], v[234:237], v[48:51]
	v_mfma_f32_16x16x32_bf16 v[16:19], v[190:193], v[234:237], v[16:19]
	v_mfma_f32_16x16x32_bf16 v[64:67], v[186:189], v[204:207], v[64:67]
	v_mfma_f32_16x16x32_bf16 v[32:35], v[194:197], v[204:207], v[32:35]
	v_mfma_f32_16x16x32_bf16 v[56:59], v[186:189], v[212:215], v[56:59]
	v_mfma_f32_16x16x32_bf16 v[24:27], v[194:197], v[212:215], v[24:27]
	v_mfma_f32_16x16x32_bf16 v[52:55], v[186:189], v[230:233], v[52:55]
	v_mfma_f32_16x16x32_bf16 v[20:23], v[194:197], v[230:233], v[20:23]
	v_mfma_f32_16x16x32_bf16 v[48:51], v[186:189], v[238:241], v[48:51]
	v_mfma_f32_16x16x32_bf16 v[16:19], v[194:197], v[238:241], v[16:19]
	s_setprio 0
	s_barrier
	s_add_i32 s28, s62, s2
	s_mov_b32 m0, s28
	ds_read_b128 v[200:203], v199 offset:49152
	ds_read_b128 v[204:207], v199 offset:50176
	ds_read_b128 v[208:211], v199 offset:51200
	ds_read_b128 v[212:215], v199 offset:52224
	ds_read_b128 v[216:219], v199 offset:53248
	ds_read_b128 v[230:233], v199 offset:54272
	ds_read_b128 v[234:237], v199 offset:55296
	ds_read_b128 v[238:241], v199 offset:56320
	global_load_lds_dwordx4 v142, s[98:99]
	s_add_i32 m0, s28, 0x2000
	s_add_u32 s28, s66, 0x40080
	s_addc_u32 s29, s67, 0
	s_add_i32 s62, s63, s2
	global_load_lds_dwordx4 v136, s[98:99]
	s_mov_b32 m0, s62
	s_nop 0
	global_load_lds_dwordx4 v142, s[28:29]
	s_add_i32 m0, s62, 0x2000
	s_nop 0
	global_load_lds_dwordx4 v136, s[28:29]
	s_mov_b32 m0, s72
	s_nop 0
	global_load_lds_dwordx4 v142, s[100:101]
	s_mov_b32 m0, s73
	s_nop 0
	global_load_lds_dwordx4 v136, s[100:101]
	s_waitcnt vmcnt(8)
	s_waitcnt lgkmcnt(0)
	s_barrier
	s_setprio 1
	s_waitcnt lgkmcnt(0)
	v_mfma_f32_16x16x32_bf16 v[108:111], v[124:127], v[200:203], v[108:111]
	v_mfma_f32_16x16x32_bf16 v[76:79], v[174:177], v[200:203], v[76:79]
	v_mfma_f32_16x16x32_bf16 v[104:107], v[124:127], v[208:211], v[104:107]
	v_mfma_f32_16x16x32_bf16 v[72:75], v[174:177], v[208:211], v[72:75]
	v_mfma_f32_16x16x32_bf16 v[100:103], v[124:127], v[216:219], v[100:103]
	v_mfma_f32_16x16x32_bf16 v[68:71], v[174:177], v[216:219], v[68:71]
	v_mfma_f32_16x16x32_bf16 v[92:95], v[124:127], v[234:237], v[92:95]
	v_mfma_f32_16x16x32_bf16 v[60:63], v[174:177], v[234:237], v[60:63]
	v_mfma_f32_16x16x32_bf16 v[108:111], v[128:131], v[204:207], v[108:111]
	v_mfma_f32_16x16x32_bf16 v[76:79], v[178:181], v[204:207], v[76:79]
	v_mfma_f32_16x16x32_bf16 v[104:107], v[128:131], v[212:215], v[104:107]
	v_mfma_f32_16x16x32_bf16 v[72:75], v[178:181], v[212:215], v[72:75]
	v_mfma_f32_16x16x32_bf16 v[100:103], v[128:131], v[230:233], v[100:103]
	v_mfma_f32_16x16x32_bf16 v[68:71], v[178:181], v[230:233], v[68:71]
	v_mfma_f32_16x16x32_bf16 v[92:95], v[128:131], v[238:241], v[92:95]
	v_mfma_f32_16x16x32_bf16 v[60:63], v[178:181], v[238:241], v[60:63]
	v_mfma_f32_16x16x32_bf16 v[44:47], v[182:185], v[200:203], v[44:47]
	v_mfma_f32_16x16x32_bf16 v[12:15], v[190:193], v[200:203], v[12:15]
	v_mfma_f32_16x16x32_bf16 v[40:43], v[182:185], v[208:211], v[40:43]
	v_mfma_f32_16x16x32_bf16 v[8:11], v[190:193], v[208:211], v[8:11]
	v_mfma_f32_16x16x32_bf16 v[36:39], v[182:185], v[216:219], v[36:39]
	v_mfma_f32_16x16x32_bf16 v[4:7], v[190:193], v[216:219], v[4:7]
	v_mfma_f32_16x16x32_bf16 v[28:31], v[182:185], v[234:237], v[28:31]
	v_mfma_f32_16x16x32_bf16 v[0:3], v[190:193], v[234:237], v[0:3]
	v_mfma_f32_16x16x32_bf16 v[44:47], v[186:189], v[204:207], v[44:47]
	v_mfma_f32_16x16x32_bf16 v[12:15], v[194:197], v[204:207], v[12:15]
	v_mfma_f32_16x16x32_bf16 v[40:43], v[186:189], v[212:215], v[40:43]
	v_mfma_f32_16x16x32_bf16 v[8:11], v[194:197], v[212:215], v[8:11]
	v_mfma_f32_16x16x32_bf16 v[36:39], v[186:189], v[230:233], v[36:39]
	v_mfma_f32_16x16x32_bf16 v[4:7], v[194:197], v[230:233], v[4:7]
	v_mfma_f32_16x16x32_bf16 v[28:31], v[186:189], v[238:241], v[28:31]
	v_mfma_f32_16x16x32_bf16 v[0:3], v[194:197], v[238:241], v[0:3]
	s_setprio 0
	s_barrier
	s_add_i32 s79, s79, 2
	s_add_u32 s77, s77, 0x100
	s_addc_u32 s78, s78, 0
	s_cmp_gt_u32 s79, 13
	s_mov_b64 s[62:63], s[64:65]
	s_cbranch_scc0 .LBB0_1083
	s_and_b64 vcc, exec, s[50:51]
	s_cbranch_vccz .LBB0_1086
	s_barrier

	.amdhsa_kernel _Z14fwd_megakernel6Params
		.amdhsa_group_segment_fixed_size 0
		.amdhsa_private_segment_fixed_size 0
		.amdhsa_kernarg_size 384
		.amdhsa_user_sgpr_count 2
		.amdhsa_user_sgpr_dispatch_ptr 0
		.amdhsa_user_sgpr_queue_ptr 0
		.amdhsa_user_sgpr_kernarg_segment_ptr 1
		.amdhsa_user_sgpr_dispatch_id 0
		.amdhsa_user_sgpr_kernarg_preload_length 0
		.amdhsa_user_sgpr_kernarg_preload_offset 0
		.amdhsa_user_sgpr_private_segment_size 0
		.amdhsa_uses_dynamic_stack 0
		.amdhsa_enable_private_segment 0
		.amdhsa_system_sgpr_workgroup_id_x 1
		.amdhsa_system_sgpr_workgroup_id_y 0
		.amdhsa_system_sgpr_workgroup_id_z 0
		.amdhsa_system_sgpr_workgroup_info 0
		.amdhsa_system_vgpr_workitem_id 2
		.amdhsa_next_free_vgpr 256
		.amdhsa_next_free_sgpr 102
		.amdhsa_accum_offset 256
		.amdhsa_reserve_vcc 1
		.amdhsa_float_round_mode_32 0
		.amdhsa_float_round_mode_16_64 0
		.amdhsa_float_denorm_mode_32 3
		.amdhsa_float_denorm_mode_16_64 3
		.amdhsa_dx10_clamp 1
		.amdhsa_ieee_mode 1
		.amdhsa_fp16_overflow 0
		.amdhsa_tg_split 0
		.amdhsa_exception_fp_ieee_invalid_op 0
		.amdhsa_exception_fp_denorm_src 0
		.amdhsa_exception_fp_ieee_div_zero 0
		.amdhsa_exception_fp_ieee_overflow 0
		.amdhsa_exception_fp_ieee_underflow 0
		.amdhsa_exception_fp_ieee_inexact 0
		.amdhsa_exception_int_div_zero 0
	.end_amdhsa_kernel

amdhsa.kernels:
  - .agpr_count:     0
    .args:
      - .offset:         0
        .size:           128
        .value_kind:     by_value
      - .offset:         128
        .size:           4
        .value_kind:     hidden_block_count_x
      - .offset:         132
        .size:           4
        .value_kind:     hidden_block_count_y
      - .offset:         136
        .size:           4
        .value_kind:     hidden_block_count_z
      - .offset:         140
        .size:           2
        .value_kind:     hidden_group_size_x
      - .offset:         142
        .size:           2
        .value_kind:     hidden_group_size_y
      - .offset:         144
        .size:           2
        .value_kind:     hidden_group_size_z
      - .offset:         146
        .size:           2
        .value_kind:     hidden_remainder_x
      - .offset:         148
        .size:           2
        .value_kind:     hidden_remainder_y
      - .offset:         150
        .size:           2
        .value_kind:     hidden_remainder_z
      - .offset:         168
        .size:           8
        .value_kind:     hidden_global_offset_x
      - .offset:         176
        .size:           8
        .value_kind:     hidden_global_offset_y
      - .offset:         184
        .size:           8
        .value_kind:     hidden_global_offset_z
      - .offset:         192
        .size:           2
        .value_kind:     hidden_grid_dims
      - .offset:         216
        .size:           8
        .value_kind:     hidden_multigrid_sync_arg
      - .offset:         248
        .size:           4
        .value_kind:     hidden_dynamic_lds_size
    .group_segment_fixed_size: 0
    .kernarg_segment_align: 8
    .kernarg_segment_size: 384
    .language:       OpenCL C
    .language_version:
      - 2
      - 0
    .max_flat_workgroup_size: 512
    .name:           _Z14fwd_megakernel6Params
    .private_segment_fixed_size: 0
    .sgpr_count:     108
    .sgpr_spill_count: 261
    .symbol:         _Z14fwd_megakernel6Params.kd
    .uniform_work_group_size: 1
    .uses_dynamic_stack: false
    .vgpr_count:     256
    .vgpr_spill_count: 0
    .wavefront_size: 64
